# speedup vs baseline: 1.0701x; 1.0105x over previous
; PHASE void norm_phase(const float* __restrict__ x, const float* __restrict__ g, u16* __restrict__ H) {
;     ...
;   for (int row = gw; row < T_; row += nw) {
;     const f32x4* xr = (const f32x4*)(x + (size_t)row * 2048);
;     f32x4 v[8];
;     float ss = 0.f;
; #pragma unroll
;     for (int i = 0; i < 8; ++i) {
;       v[i] = xr[lane + 64 * i];
;       ss += v[i].x * v[i].x + v[i].y * v[i].y + v[i].z * v[i].z + v[i].w * v[i].w;
;     }
;     ss = wave_sum(ss);
;     const float rs = rsqrtf(ss * (1.f / 2048.f) + 1e-6f);
.LBB0_171:
	v_mov_b32_e32 v0, v178
	s_waitcnt lgkmcnt(0)
	v_mov_b32_e32 v1, v178
	s_mov_b32 s6, 0x8000
	v_ashrrev_i32_e32 v1, 6, v1
	v_add_u32_e32 v32, s43, v1
	v_cmp_gt_i32_e32 vcc, s6, v32
	s_and_saveexec_b64 s[6:7], vcc
	s_mov_b32 s16, 0x800000
	s_cbranch_execz .LBB0_170
	v_and_b32_e32 v2, 63, v0
	v_lshlrev_b32_e32 v156, 4, v2
	v_or_b32_e32 v0, 0x1000, v156
	v_mov_b32_e32 v1, v157
	s_load_dword s8, s[86:87], 0x0
	v_lshl_add_u64 v[36:37], s[0:1], 0, v[0:1]
	v_or_b32_e32 v0, 0x1400, v156
	v_lshl_add_u64 v[38:39], s[0:1], 0, v[0:1]
	v_or_b32_e32 v0, 0x1800, v156
	v_lshl_add_u64 v[40:41], s[0:1], 0, v[0:1]
	v_or_b32_e32 v0, 0x1c00, v156
	v_ashrrev_i32_e32 v33, 31, v32
	v_lshl_add_u64 v[42:43], s[0:1], 0, v[0:1]
	v_lshlrev_b64 v[0:1], 12, v[32:33]
	v_lshl_or_b32 v0, v2, 3, v0
	s_waitcnt lgkmcnt(0)
	s_lshl_b32 s8, s8, 2
	v_lshl_add_u64 v[44:45], s[64:65], 0, v[0:1]
	v_lshlrev_b64 v[0:1], 13, v[32:33]
	s_ashr_i32 s9, s8, 31
	v_or_b32_e32 v0, v0, v156
	v_lshl_add_u64 v[34:35], s[0:1], 0, v[156:157]
	s_lshl_b64 s[10:11], s[8:9], 12
	v_lshl_add_u64 v[46:47], s[2:3], 0, v[0:1]
	s_lshl_b64 s[12:13], s[8:9], 13
	s_mov_b64 s[14:15], 0
	global_load_dwordx4 v[68:71], v[34:35], off
	global_load_dwordx4 v[72:75], v[34:35], off offset:1024
	global_load_dwordx4 v[76:79], v[34:35], off offset:2048
	global_load_dwordx4 v[80:83], v[34:35], off offset:3072
	global_load_dwordx4 v[84:87], v[36:37], off
	global_load_dwordx4 v[88:91], v[38:39], off
	global_load_dwordx4 v[92:95], v[40:41], off
	global_load_dwordx4 v[96:99], v[42:43], off
.LBB0_173:
	global_load_dwordx4 v[0:3], v[46:47], off offset:-4096
	global_load_dwordx4 v[8:11], v[46:47], off offset:-3072
	global_load_dwordx4 v[12:15], v[46:47], off offset:-2048
	global_load_dwordx4 v[16:19], v[46:47], off offset:-1024
	global_load_dwordx4 v[20:23], v[46:47], off
	global_load_dwordx4 v[100:103], v[46:47], off offset:1024
	global_load_dwordx4 v[104:107], v[46:47], off offset:2048
	global_load_dwordx4 v[108:111], v[46:47], off offset:3072
	v_add_u32_e32 v32, s8, v32
	s_waitcnt vmcnt(7)
	v_mul_f32_e32 v4, v1, v1
	s_waitcnt vmcnt(6)
	v_mul_f32_e32 v5, v9, v9
	v_fmac_f32_e32 v4, v0, v0
	v_fmac_f32_e32 v5, v8, v8
	v_fmac_f32_e32 v4, v2, v2
	v_fmac_f32_e32 v5, v10, v10
	v_fmac_f32_e32 v4, v3, v3
	v_fmac_f32_e32 v5, v11, v11
	v_add_f32_e32 v4, v4, v5
	s_waitcnt vmcnt(5)
	v_mul_f32_e32 v5, v13, v13
	v_fmac_f32_e32 v5, v12, v12
	v_fmac_f32_e32 v5, v14, v14
	v_fmac_f32_e32 v5, v15, v15
	v_add_f32_e32 v4, v4, v5
	s_waitcnt vmcnt(4)
	v_mul_f32_e32 v5, v17, v17
	v_fmac_f32_e32 v5, v16, v16
	v_fmac_f32_e32 v5, v18, v18
	v_fmac_f32_e32 v5, v19, v19
	v_add_f32_e32 v28, v4, v5
	s_waitcnt vmcnt(2)
	v_mov_b64_e32 v[4:5], v[100:101]
	v_mov_b64_e32 v[6:7], v[102:103]
	v_mov_b32_e32 v55, v2
	v_mov_b32_e32 v2, v1
	v_mov_b32_e32 v54, v0
	s_waitcnt vmcnt(3)
	v_mov_b32_e32 v26, v21
	s_waitcnt vmcnt(2)
	v_mov_b32_e32 v27, v5
	v_mov_b32_e32 v24, v20
	v_mov_b32_e32 v25, v4
	v_pk_mul_f32 v[26:27], v[26:27], v[26:27]
	s_nop 0
	v_pk_fma_f32 v[24:25], v[24:25], v[24:25], v[26:27]
	v_mov_b32_e32 v26, v22
	v_mov_b32_e32 v27, v6
	v_pk_fma_f32 v[24:25], v[26:27], v[26:27], v[24:25]
	v_mov_b32_e32 v26, v23
	v_mov_b32_e32 v27, v7
	v_pk_fma_f32 v[24:25], v[26:27], v[26:27], v[24:25]
	s_nop 0
	v_add_f32_e32 v24, v28, v24
	v_add_f32_e32 v33, v24, v25
	s_waitcnt vmcnt(0)
	v_mov_b64_e32 v[28:29], v[104:105]
	v_mov_b64_e32 v[30:31], v[106:107]
	v_mov_b64_e32 v[24:25], v[108:109]
	v_mov_b64_e32 v[26:27], v[110:111]
	v_lshl_add_u64 v[46:47], v[46:47], 0, s[12:13]
	v_mov_b32_e32 v50, v29
	v_mov_b32_e32 v51, v25
	v_mov_b32_e32 v48, v28
	v_mov_b32_e32 v49, v24
	v_pk_mul_f32 v[50:51], v[50:51], v[50:51]
	s_nop 0
	v_pk_fma_f32 v[48:49], v[48:49], v[48:49], v[50:51]
	v_mov_b32_e32 v50, v30
	v_mov_b32_e32 v51, v26
	v_pk_fma_f32 v[48:49], v[50:51], v[50:51], v[48:49]
	v_mov_b32_e32 v50, v31
	v_mov_b32_e32 v51, v27
	v_pk_fma_f32 v[48:49], v[50:51], v[50:51], v[48:49]
	s_nop 0
	v_add_f32_e32 v33, v33, v48
	v_mov_b32_e32 v48, v184
	v_add_f32_e32 v33, v33, v49
	v_lshlrev_b32_e32 v48, 2, v48
	v_xor_b32_e32 v48, 0x80, v48
	ds_bpermute_b32 v48, v48, v33
	s_waitcnt lgkmcnt(0)
	v_add_f32_e32 v33, v33, v48
	v_mov_b32_e32 v48, v184
	s_nop 0
	v_lshlrev_b32_e32 v48, 2, v48
	v_xor_b32_e32 v48, 64, v48
	ds_bpermute_b32 v48, v48, v33
	s_waitcnt lgkmcnt(0)
	v_add_f32_e32 v33, v33, v48
	v_mov_b32_e32 v48, v184
	s_nop 0
	v_lshlrev_b32_e32 v48, 2, v48
	v_xor_b32_e32 v48, 32, v48
	ds_bpermute_b32 v48, v48, v33
	s_waitcnt lgkmcnt(0)
	v_add_f32_e32 v33, v33, v48
	v_mov_b32_e32 v48, v184
	s_nop 0
	v_lshlrev_b32_e32 v48, 2, v48
	v_xor_b32_e32 v48, 16, v48
	ds_bpermute_b32 v48, v48, v33
	s_waitcnt lgkmcnt(0)
	v_add_f32_e32 v33, v33, v48
	v_mov_b32_e32 v48, v184
	s_nop 0
	v_lshlrev_b32_e32 v48, 2, v48
	v_xor_b32_e32 v48, 8, v48
	ds_bpermute_b32 v48, v48, v33
	s_waitcnt lgkmcnt(0)
	v_add_f32_e32 v33, v33, v48
	v_mov_b32_e32 v48, v184
	s_nop 0
	v_lshlrev_b32_e32 v48, 2, v48
	v_xor_b32_e32 v48, 4, v48
	ds_bpermute_b32 v48, v48, v33
	s_waitcnt lgkmcnt(0)
; DEV unsigned pack2(float a, float b) { return (unsigned)f2bf(a) | ((unsigned)f2bf(b) << 16); }
; PHASE void norm_phase(const float* __restrict__ x, const float* __restrict__ g, u16* __restrict__ H) {
;     ...
;     const float rs = rsqrtf(ss * (1.f / 2048.f) + 1e-6f);
; #pragma unroll
;     for (int i = 0; i < 8; ++i) {
;       f32x4 gg = ((const f32x4*)g)[lane + 64 * i];
;       u32x2 o;
;       o.x = pack2(v[i].x * rs * gg.x, v[i].y * rs * gg.y);
;       o.y = pack2(v[i].z * rs * gg.z, v[i].w * rs * gg.w);
;       *(u32x2*)(H + (size_t)row * 2048 + (size_t)(lane + 64 * i) * 4) = o;
	v_add_f32_e32 v33, v33, v48
	v_fmamk_f32 v33, v33, 0x3a000000, v179
	v_cmp_gt_f32_e32 vcc, s16, v33
	v_mul_f32_e32 v48, 0x4b800000, v33
	s_nop 0
	v_cndmask_b32_e32 v33, v33, v48, vcc
	v_rsq_f32_e32 v33, v33
	s_nop 0
	v_mul_f32_e32 v48, 0x45800000, v33
	v_cndmask_b32_e32 v52, v33, v48, vcc
	v_mov_b64_e32 v[48:49], v[68:69]
	v_mov_b64_e32 v[50:51], v[70:71]
	v_pk_mul_f32 v[0:1], v[2:3], v[52:53] op_sel_hi:[1,0]
	v_pk_mul_f32 v[54:55], v[54:55], v[52:53] op_sel_hi:[1,0]
	v_cmp_lt_i32_e32 vcc, s71, v32
	s_or_b64 s[14:15], vcc, s[14:15]
	v_mov_b32_e32 v57, v50
	v_mov_b32_e32 v50, v49
	v_mov_b32_e32 v56, v48
	v_pk_mul_f32 v[0:1], v[50:51], v[0:1]
	v_pk_mul_f32 v[54:55], v[56:57], v[54:55]
	v_and_b32_sdwa v33, v1, v182 dst_sel:DWORD dst_unused:UNUSED_PAD src0_sel:WORD_1 src1_sel:DWORD
	v_and_b32_sdwa v48, v0, v182 dst_sel:DWORD dst_unused:UNUSED_PAD src0_sel:WORD_1 src1_sel:DWORD
	v_and_b32_sdwa v2, v55, v182 dst_sel:DWORD dst_unused:UNUSED_PAD src0_sel:WORD_1 src1_sel:DWORD
	v_and_b32_sdwa v3, v54, v182 dst_sel:DWORD dst_unused:UNUSED_PAD src0_sel:WORD_1 src1_sel:DWORD
	v_add3_u32 v1, v1, v33, s71
	v_add3_u32 v0, v0, v48, s71
	v_add3_u32 v3, v54, v3, s71
	v_add3_u32 v2, v55, v2, s71
	v_and_b32_e32 v1, 0xffff0000, v1
	v_and_b32_e32 v0, 0xffff0000, v0
	v_or_b32_sdwa v1, v1, v2 dst_sel:DWORD dst_unused:UNUSED_PAD src0_sel:DWORD src1_sel:WORD_1
	v_or_b32_sdwa v0, v0, v3 dst_sel:DWORD dst_unused:UNUSED_PAD src0_sel:DWORD src1_sel:WORD_1
	global_store_dwordx2 v[44:45], v[0:1], off
	v_mov_b64_e32 v[0:1], v[72:73]
	v_mov_b64_e32 v[2:3], v[74:75]
	v_mov_b32_e32 v49, v10
	v_mov_b32_e32 v10, v9
	v_mov_b32_e32 v48, v8
	v_pk_mul_f32 v[8:9], v[10:11], v[52:53] op_sel_hi:[1,0]
	v_pk_mul_f32 v[48:49], v[48:49], v[52:53] op_sel_hi:[1,0]
	v_mov_b32_e32 v51, v2
	v_mov_b32_e32 v2, v1
	v_mov_b32_e32 v50, v0
	v_pk_mul_f32 v[0:1], v[2:3], v[8:9]
	v_pk_mul_f32 v[48:49], v[50:51], v[48:49]
	v_and_b32_sdwa v8, v1, v182 dst_sel:DWORD dst_unused:UNUSED_PAD src0_sel:WORD_1 src1_sel:DWORD
	v_and_b32_sdwa v9, v0, v182 dst_sel:DWORD dst_unused:UNUSED_PAD src0_sel:WORD_1 src1_sel:DWORD
	v_and_b32_sdwa v2, v49, v182 dst_sel:DWORD dst_unused:UNUSED_PAD src0_sel:WORD_1 src1_sel:DWORD
	v_and_b32_sdwa v3, v48, v182 dst_sel:DWORD dst_unused:UNUSED_PAD src0_sel:WORD_1 src1_sel:DWORD
	v_add3_u32 v1, v1, v8, s71
	v_add3_u32 v0, v0, v9, s71
	v_add3_u32 v3, v48, v3, s71
	v_add3_u32 v2, v49, v2, s71
	v_and_b32_e32 v1, 0xffff0000, v1
	v_and_b32_e32 v0, 0xffff0000, v0
	v_or_b32_sdwa v1, v1, v2 dst_sel:DWORD dst_unused:UNUSED_PAD src0_sel:DWORD src1_sel:WORD_1
	v_or_b32_sdwa v0, v0, v3 dst_sel:DWORD dst_unused:UNUSED_PAD src0_sel:DWORD src1_sel:WORD_1
	global_store_dwordx2 v[44:45], v[0:1], off offset:512
	v_mov_b64_e32 v[0:1], v[76:77]
	v_mov_b64_e32 v[2:3], v[78:79]
	v_mov_b32_e32 v8, v12
	v_mov_b32_e32 v9, v14
	v_pk_mul_f32 v[8:9], v[8:9], v[52:53] op_sel_hi:[1,0]
	v_mov_b32_e32 v14, v13
	v_mov_b32_e32 v10, v0
	v_mov_b32_e32 v11, v2
	v_pk_mul_f32 v[8:9], v[10:11], v[8:9]
	v_pk_mul_f32 v[10:11], v[14:15], v[52:53] op_sel_hi:[1,0]
	v_mov_b32_e32 v2, v1
	v_pk_mul_f32 v[0:1], v[2:3], v[10:11]
	v_and_b32_sdwa v2, v9, v182 dst_sel:DWORD dst_unused:UNUSED_PAD src0_sel:WORD_1 src1_sel:DWORD
	v_and_b32_sdwa v3, v8, v182 dst_sel:DWORD dst_unused:UNUSED_PAD src0_sel:WORD_1 src1_sel:DWORD
	v_add3_u32 v3, v8, v3, s71
	v_add3_u32 v2, v9, v2, s71
	v_and_b32_sdwa v8, v1, v182 dst_sel:DWORD dst_unused:UNUSED_PAD src0_sel:WORD_1 src1_sel:DWORD
	v_and_b32_sdwa v9, v0, v182 dst_sel:DWORD dst_unused:UNUSED_PAD src0_sel:WORD_1 src1_sel:DWORD
	v_add3_u32 v1, v1, v8, s71
	v_add3_u32 v0, v0, v9, s71
	v_and_b32_e32 v1, 0xffff0000, v1
	v_and_b32_e32 v0, 0xffff0000, v0
	v_or_b32_sdwa v1, v1, v2 dst_sel:DWORD dst_unused:UNUSED_PAD src0_sel:DWORD src1_sel:WORD_1
	v_or_b32_sdwa v0, v0, v3 dst_sel:DWORD dst_unused:UNUSED_PAD src0_sel:DWORD src1_sel:WORD_1
	global_store_dwordx2 v[44:45], v[0:1], off offset:1024
	v_mov_b64_e32 v[0:1], v[80:81]
	v_mov_b64_e32 v[2:3], v[82:83]
	v_mov_b32_e32 v8, v16
	v_mov_b32_e32 v9, v18
	v_pk_mul_f32 v[8:9], v[8:9], v[52:53] op_sel_hi:[1,0]
	v_mov_b32_e32 v18, v17
	v_mov_b32_e32 v10, v0
	v_mov_b32_e32 v11, v2
	v_pk_mul_f32 v[8:9], v[10:11], v[8:9]
	v_pk_mul_f32 v[10:11], v[18:19], v[52:53] op_sel_hi:[1,0]
	v_mov_b32_e32 v2, v1
	v_pk_mul_f32 v[0:1], v[2:3], v[10:11]
	v_and_b32_sdwa v2, v9, v182 dst_sel:DWORD dst_unused:UNUSED_PAD src0_sel:WORD_1 src1_sel:DWORD
	v_and_b32_sdwa v3, v8, v182 dst_sel:DWORD dst_unused:UNUSED_PAD src0_sel:WORD_1 src1_sel:DWORD
	v_add3_u32 v3, v8, v3, s71
	v_add3_u32 v2, v9, v2, s71
	v_and_b32_sdwa v8, v1, v182 dst_sel:DWORD dst_unused:UNUSED_PAD src0_sel:WORD_1 src1_sel:DWORD
	v_and_b32_sdwa v9, v0, v182 dst_sel:DWORD dst_unused:UNUSED_PAD src0_sel:WORD_1 src1_sel:DWORD
	v_add3_u32 v1, v1, v8, s71
	v_add3_u32 v0, v0, v9, s71
	v_and_b32_e32 v1, 0xffff0000, v1
	v_and_b32_e32 v0, 0xffff0000, v0
	v_or_b32_sdwa v1, v1, v2 dst_sel:DWORD dst_unused:UNUSED_PAD src0_sel:DWORD src1_sel:WORD_1
	v_or_b32_sdwa v0, v0, v3 dst_sel:DWORD dst_unused:UNUSED_PAD src0_sel:DWORD src1_sel:WORD_1
; DEV unsigned pack2(float a, float b) { return (unsigned)f2bf(a) | ((unsigned)f2bf(b) << 16); }
; PHASE void norm_phase(const float* __restrict__ x, const float* __restrict__ g, u16* __restrict__ H) {
;     ...
;     for (int i = 0; i < 8; ++i) {
;       f32x4 gg = ((const f32x4*)g)[lane + 64 * i];
;       u32x2 o;
;       o.x = pack2(v[i].x * rs * gg.x, v[i].y * rs * gg.y);
;       o.y = pack2(v[i].z * rs * gg.z, v[i].w * rs * gg.w);
;       *(u32x2*)(H + (size_t)row * 2048 + (size_t)(lane + 64 * i) * 4) = o;
;     }
;   }
	global_store_dwordx2 v[44:45], v[0:1], off offset:1536
	v_mov_b64_e32 v[0:1], v[84:85]
	v_mov_b64_e32 v[2:3], v[86:87]
	v_mov_b32_e32 v8, v20
	v_mov_b32_e32 v9, v22
	v_pk_mul_f32 v[8:9], v[8:9], v[52:53] op_sel_hi:[1,0]
	v_mov_b32_e32 v22, v21
	v_mov_b32_e32 v10, v0
	v_mov_b32_e32 v11, v2
	v_pk_mul_f32 v[8:9], v[8:9], v[10:11]
	v_pk_mul_f32 v[10:11], v[22:23], v[52:53] op_sel_hi:[1,0]
	v_mov_b32_e32 v2, v1
	v_pk_mul_f32 v[0:1], v[10:11], v[2:3]
	v_and_b32_sdwa v2, v9, v182 dst_sel:DWORD dst_unused:UNUSED_PAD src0_sel:WORD_1 src1_sel:DWORD
	v_and_b32_sdwa v3, v8, v182 dst_sel:DWORD dst_unused:UNUSED_PAD src0_sel:WORD_1 src1_sel:DWORD
	v_add3_u32 v3, v8, v3, s71
	v_add3_u32 v2, v9, v2, s71
	v_and_b32_sdwa v8, v1, v182 dst_sel:DWORD dst_unused:UNUSED_PAD src0_sel:WORD_1 src1_sel:DWORD
	v_and_b32_sdwa v9, v0, v182 dst_sel:DWORD dst_unused:UNUSED_PAD src0_sel:WORD_1 src1_sel:DWORD
	v_add3_u32 v1, v1, v8, s71
	v_add3_u32 v0, v0, v9, s71
	v_and_b32_e32 v1, 0xffff0000, v1
	v_and_b32_e32 v0, 0xffff0000, v0
	v_or_b32_sdwa v1, v1, v2 dst_sel:DWORD dst_unused:UNUSED_PAD src0_sel:DWORD src1_sel:WORD_1
	v_or_b32_sdwa v0, v0, v3 dst_sel:DWORD dst_unused:UNUSED_PAD src0_sel:DWORD src1_sel:WORD_1
	global_store_dwordx2 v[44:45], v[0:1], off offset:2048
	v_mov_b64_e32 v[0:1], v[88:89]
	v_mov_b64_e32 v[2:3], v[90:91]
	v_mov_b32_e32 v9, v6
	v_mov_b32_e32 v6, v5
	v_mov_b32_e32 v8, v4
	v_pk_mul_f32 v[4:5], v[6:7], v[52:53] op_sel_hi:[1,0]
	v_pk_mul_f32 v[8:9], v[8:9], v[52:53] op_sel_hi:[1,0]
	v_mov_b32_e32 v11, v2
	v_mov_b32_e32 v2, v1
	v_mov_b32_e32 v10, v0
	v_pk_mul_f32 v[0:1], v[4:5], v[2:3]
	v_pk_mul_f32 v[8:9], v[8:9], v[10:11]
	v_and_b32_sdwa v4, v1, v182 dst_sel:DWORD dst_unused:UNUSED_PAD src0_sel:WORD_1 src1_sel:DWORD
	v_and_b32_sdwa v5, v0, v182 dst_sel:DWORD dst_unused:UNUSED_PAD src0_sel:WORD_1 src1_sel:DWORD
	v_and_b32_sdwa v2, v9, v182 dst_sel:DWORD dst_unused:UNUSED_PAD src0_sel:WORD_1 src1_sel:DWORD
	v_and_b32_sdwa v3, v8, v182 dst_sel:DWORD dst_unused:UNUSED_PAD src0_sel:WORD_1 src1_sel:DWORD
	v_add3_u32 v1, v1, v4, s71
	v_add3_u32 v0, v0, v5, s71
	v_add3_u32 v3, v8, v3, s71
	v_add3_u32 v2, v9, v2, s71
	v_and_b32_e32 v1, 0xffff0000, v1
	v_and_b32_e32 v0, 0xffff0000, v0
	v_or_b32_sdwa v1, v1, v2 dst_sel:DWORD dst_unused:UNUSED_PAD src0_sel:DWORD src1_sel:WORD_1
	v_or_b32_sdwa v0, v0, v3 dst_sel:DWORD dst_unused:UNUSED_PAD src0_sel:DWORD src1_sel:WORD_1
	global_store_dwordx2 v[44:45], v[0:1], off offset:2560
	v_mov_b64_e32 v[0:1], v[92:93]
	v_mov_b64_e32 v[2:3], v[94:95]
	v_mov_b32_e32 v4, v28
	v_mov_b32_e32 v5, v30
	v_pk_mul_f32 v[4:5], v[4:5], v[52:53] op_sel_hi:[1,0]
	v_mov_b32_e32 v30, v29
	v_mov_b32_e32 v6, v0
	v_mov_b32_e32 v7, v2
	v_pk_mul_f32 v[4:5], v[4:5], v[6:7]
	v_pk_mul_f32 v[6:7], v[30:31], v[52:53] op_sel_hi:[1,0]
	v_mov_b32_e32 v2, v1
	v_pk_mul_f32 v[0:1], v[6:7], v[2:3]
	v_and_b32_sdwa v2, v5, v182 dst_sel:DWORD dst_unused:UNUSED_PAD src0_sel:WORD_1 src1_sel:DWORD
	v_and_b32_sdwa v3, v4, v182 dst_sel:DWORD dst_unused:UNUSED_PAD src0_sel:WORD_1 src1_sel:DWORD
	v_add3_u32 v3, v4, v3, s71
	v_add3_u32 v2, v5, v2, s71
	v_and_b32_sdwa v4, v1, v182 dst_sel:DWORD dst_unused:UNUSED_PAD src0_sel:WORD_1 src1_sel:DWORD
	v_and_b32_sdwa v5, v0, v182 dst_sel:DWORD dst_unused:UNUSED_PAD src0_sel:WORD_1 src1_sel:DWORD
	v_add3_u32 v1, v1, v4, s71
	v_add3_u32 v0, v0, v5, s71
	v_and_b32_e32 v1, 0xffff0000, v1
	v_and_b32_e32 v0, 0xffff0000, v0
	v_or_b32_sdwa v1, v1, v2 dst_sel:DWORD dst_unused:UNUSED_PAD src0_sel:DWORD src1_sel:WORD_1
	v_or_b32_sdwa v0, v0, v3 dst_sel:DWORD dst_unused:UNUSED_PAD src0_sel:DWORD src1_sel:WORD_1
	global_store_dwordx2 v[44:45], v[0:1], off offset:3072
	v_mov_b64_e32 v[0:1], v[96:97]
	v_mov_b64_e32 v[2:3], v[98:99]
	v_mov_b32_e32 v4, v24
	v_mov_b32_e32 v5, v26
	v_pk_mul_f32 v[4:5], v[4:5], v[52:53] op_sel_hi:[1,0]
	v_mov_b32_e32 v26, v25
	v_mov_b32_e32 v6, v0
	v_mov_b32_e32 v7, v2
	v_pk_mul_f32 v[4:5], v[4:5], v[6:7]
	v_pk_mul_f32 v[6:7], v[26:27], v[52:53] op_sel_hi:[1,0]
	v_mov_b32_e32 v2, v1
	v_pk_mul_f32 v[0:1], v[6:7], v[2:3]
	v_and_b32_sdwa v2, v5, v182 dst_sel:DWORD dst_unused:UNUSED_PAD src0_sel:WORD_1 src1_sel:DWORD
	v_and_b32_sdwa v3, v4, v182 dst_sel:DWORD dst_unused:UNUSED_PAD src0_sel:WORD_1 src1_sel:DWORD
	v_add3_u32 v3, v4, v3, s71
	v_add3_u32 v2, v5, v2, s71
	v_and_b32_sdwa v4, v1, v182 dst_sel:DWORD dst_unused:UNUSED_PAD src0_sel:WORD_1 src1_sel:DWORD
	v_and_b32_sdwa v5, v0, v182 dst_sel:DWORD dst_unused:UNUSED_PAD src0_sel:WORD_1 src1_sel:DWORD
	v_add3_u32 v1, v1, v4, s71
	v_add3_u32 v0, v0, v5, s71
	v_and_b32_e32 v1, 0xffff0000, v1
	v_and_b32_e32 v0, 0xffff0000, v0
	v_or_b32_sdwa v1, v1, v2 dst_sel:DWORD dst_unused:UNUSED_PAD src0_sel:DWORD src1_sel:WORD_1
	v_or_b32_sdwa v0, v0, v3 dst_sel:DWORD dst_unused:UNUSED_PAD src0_sel:DWORD src1_sel:WORD_1
	global_store_dwordx2 v[44:45], v[0:1], off offset:3584
	v_lshl_add_u64 v[44:45], v[44:45], 0, s[10:11]
	s_andn2_b64 exec, exec, s[14:15]
	s_cbranch_execnz .LBB0_173
	s_branch .LBB0_170

; PHASE void norm_phase(const float* __restrict__ x, const float* __restrict__ g, u16* __restrict__ H) {
;     ...
;   for (int row = gw; row < T_; row += nw) {
;     const f32x4* xr = (const f32x4*)(x + (size_t)row * 2048);
;     f32x4 v[8];
;     float ss = 0.f;
; #pragma unroll
;     for (int i = 0; i < 8; ++i) {
;       v[i] = xr[lane + 64 * i];
;       ss += v[i].x * v[i].x + v[i].y * v[i].y + v[i].z * v[i].z + v[i].w * v[i].w;
;     }
;     ss = wave_sum(ss);
;     const float rs = rsqrtf(ss * (1.f / 2048.f) + 1e-6f);
.LBB0_235:
	v_mov_b32_e32 v0, v178
	s_waitcnt lgkmcnt(0)
	v_mov_b32_e32 v1, v178
	s_mov_b32 s4, 0x8000
	v_ashrrev_i32_e32 v1, 6, v1
	v_add_u32_e32 v32, s43, v1
	v_cmp_gt_i32_e32 vcc, s4, v32
	s_and_saveexec_b64 s[4:5], vcc
	s_mov_b32 s14, 0x800000
	s_cbranch_execz .LBB0_234
	v_and_b32_e32 v2, 63, v0
	v_lshlrev_b32_e32 v156, 4, v2
	v_or_b32_e32 v0, 0x1000, v156
	v_mov_b32_e32 v1, v157
	s_load_dword s6, s[86:87], 0x0
	v_lshl_add_u64 v[36:37], s[0:1], 0, v[0:1]
	v_or_b32_e32 v0, 0x1400, v156
	v_lshl_add_u64 v[38:39], s[0:1], 0, v[0:1]
	v_or_b32_e32 v0, 0x1800, v156
	v_lshl_add_u64 v[40:41], s[0:1], 0, v[0:1]
	v_or_b32_e32 v0, 0x1c00, v156
	v_ashrrev_i32_e32 v33, 31, v32
	v_lshl_add_u64 v[42:43], s[0:1], 0, v[0:1]
	v_lshlrev_b64 v[0:1], 12, v[32:33]
	v_lshl_or_b32 v0, v2, 3, v0
	s_waitcnt lgkmcnt(0)
	s_lshl_b32 s6, s6, 2
	v_lshl_add_u64 v[44:45], s[64:65], 0, v[0:1]
	v_lshlrev_b64 v[0:1], 13, v[32:33]
	v_readlane_b32 s10, v251, 11
	s_ashr_i32 s7, s6, 31
	v_or_b32_e32 v0, v0, v156
	v_readlane_b32 s11, v251, 12
	v_lshl_add_u64 v[34:35], s[0:1], 0, v[156:157]
	s_lshl_b64 s[8:9], s[6:7], 12
	v_lshl_add_u64 v[46:47], s[10:11], 0, v[0:1]
	s_lshl_b64 s[10:11], s[6:7], 13
	s_mov_b64 s[12:13], 0
	global_load_dwordx4 v[68:71], v[34:35], off
	global_load_dwordx4 v[72:75], v[34:35], off offset:1024
	global_load_dwordx4 v[76:79], v[34:35], off offset:2048
	global_load_dwordx4 v[80:83], v[34:35], off offset:3072
	global_load_dwordx4 v[84:87], v[36:37], off
	global_load_dwordx4 v[88:91], v[38:39], off
	global_load_dwordx4 v[92:95], v[40:41], off
	global_load_dwordx4 v[96:99], v[42:43], off
.LBB0_237:
	global_load_dwordx4 v[0:3], v[46:47], off offset:-4096
	global_load_dwordx4 v[8:11], v[46:47], off offset:-3072
	global_load_dwordx4 v[12:15], v[46:47], off offset:-2048
	global_load_dwordx4 v[16:19], v[46:47], off offset:-1024
	global_load_dwordx4 v[20:23], v[46:47], off
	global_load_dwordx4 v[100:103], v[46:47], off offset:1024
	global_load_dwordx4 v[104:107], v[46:47], off offset:2048
	global_load_dwordx4 v[108:111], v[46:47], off offset:3072
	v_add_u32_e32 v32, s6, v32
	s_waitcnt vmcnt(7)
	v_mul_f32_e32 v4, v1, v1
	s_waitcnt vmcnt(6)
	v_mul_f32_e32 v5, v9, v9
	v_fmac_f32_e32 v4, v0, v0
	v_fmac_f32_e32 v5, v8, v8
	v_fmac_f32_e32 v4, v2, v2
	v_fmac_f32_e32 v5, v10, v10
	v_fmac_f32_e32 v4, v3, v3
	v_fmac_f32_e32 v5, v11, v11
	v_add_f32_e32 v4, v4, v5
	s_waitcnt vmcnt(5)
	v_mul_f32_e32 v5, v13, v13
	v_fmac_f32_e32 v5, v12, v12
	v_fmac_f32_e32 v5, v14, v14
	v_fmac_f32_e32 v5, v15, v15
	v_add_f32_e32 v4, v4, v5
	s_waitcnt vmcnt(4)
	v_mul_f32_e32 v5, v17, v17
	v_fmac_f32_e32 v5, v16, v16
	v_fmac_f32_e32 v5, v18, v18
	v_fmac_f32_e32 v5, v19, v19
	v_add_f32_e32 v28, v4, v5
	s_waitcnt vmcnt(2)
	v_mov_b64_e32 v[4:5], v[100:101]
	v_mov_b64_e32 v[6:7], v[102:103]
	v_mov_b32_e32 v55, v2
	v_mov_b32_e32 v2, v1
	v_mov_b32_e32 v54, v0
	s_waitcnt vmcnt(3)
	v_mov_b32_e32 v26, v21
	s_waitcnt vmcnt(2)
	v_mov_b32_e32 v27, v5
	v_mov_b32_e32 v24, v20
	v_mov_b32_e32 v25, v4
	v_pk_mul_f32 v[26:27], v[26:27], v[26:27]
	s_nop 0
	v_pk_fma_f32 v[24:25], v[24:25], v[24:25], v[26:27]
	v_mov_b32_e32 v26, v22
	v_mov_b32_e32 v27, v6
	v_pk_fma_f32 v[24:25], v[26:27], v[26:27], v[24:25]
	v_mov_b32_e32 v26, v23
	v_mov_b32_e32 v27, v7
	v_pk_fma_f32 v[24:25], v[26:27], v[26:27], v[24:25]
	s_nop 0
	v_add_f32_e32 v24, v28, v24
	v_add_f32_e32 v33, v24, v25
	s_waitcnt vmcnt(0)
	v_mov_b64_e32 v[28:29], v[104:105]
	v_mov_b64_e32 v[30:31], v[106:107]
	v_mov_b64_e32 v[24:25], v[108:109]
	v_mov_b64_e32 v[26:27], v[110:111]
	v_lshl_add_u64 v[46:47], v[46:47], 0, s[10:11]
	v_mov_b32_e32 v50, v29
	v_mov_b32_e32 v51, v25
	v_mov_b32_e32 v48, v28
	v_mov_b32_e32 v49, v24
	v_pk_mul_f32 v[50:51], v[50:51], v[50:51]
	s_nop 0
	v_pk_fma_f32 v[48:49], v[48:49], v[48:49], v[50:51]
	v_mov_b32_e32 v50, v30
	v_mov_b32_e32 v51, v26
	v_pk_fma_f32 v[48:49], v[50:51], v[50:51], v[48:49]
	v_mov_b32_e32 v50, v31
	v_mov_b32_e32 v51, v27
	v_pk_fma_f32 v[48:49], v[50:51], v[50:51], v[48:49]
	s_nop 0
	v_add_f32_e32 v33, v33, v48
	v_mov_b32_e32 v48, v184
	v_add_f32_e32 v33, v33, v49
	v_lshlrev_b32_e32 v48, 2, v48
	v_xor_b32_e32 v48, 0x80, v48
	ds_bpermute_b32 v48, v48, v33
	s_waitcnt lgkmcnt(0)
	v_add_f32_e32 v33, v33, v48
	v_mov_b32_e32 v48, v184
	s_nop 0
	v_lshlrev_b32_e32 v48, 2, v48
	v_xor_b32_e32 v48, 64, v48
	ds_bpermute_b32 v48, v48, v33
	s_waitcnt lgkmcnt(0)
	v_add_f32_e32 v33, v33, v48
	v_mov_b32_e32 v48, v184
	s_nop 0
	v_lshlrev_b32_e32 v48, 2, v48
	v_xor_b32_e32 v48, 32, v48
	ds_bpermute_b32 v48, v48, v33
	s_waitcnt lgkmcnt(0)
	v_add_f32_e32 v33, v33, v48
	v_mov_b32_e32 v48, v184
	s_nop 0
	v_lshlrev_b32_e32 v48, 2, v48
	v_xor_b32_e32 v48, 16, v48
	ds_bpermute_b32 v48, v48, v33
	s_waitcnt lgkmcnt(0)
	v_add_f32_e32 v33, v33, v48
	v_mov_b32_e32 v48, v184
	s_nop 0
	v_lshlrev_b32_e32 v48, 2, v48
	v_xor_b32_e32 v48, 8, v48
	ds_bpermute_b32 v48, v48, v33
	s_waitcnt lgkmcnt(0)
	v_add_f32_e32 v33, v33, v48
	v_mov_b32_e32 v48, v184
	s_nop 0
	v_lshlrev_b32_e32 v48, 2, v48
	v_xor_b32_e32 v48, 4, v48
	ds_bpermute_b32 v48, v48, v33
	s_waitcnt lgkmcnt(0)
; DEV unsigned pack2(float a, float b) { return (unsigned)f2bf(a) | ((unsigned)f2bf(b) << 16); }
; PHASE void norm_phase(const float* __restrict__ x, const float* __restrict__ g, u16* __restrict__ H) {
;     ...
;     const float rs = rsqrtf(ss * (1.f / 2048.f) + 1e-6f);
; #pragma unroll
;     for (int i = 0; i < 8; ++i) {
;       f32x4 gg = ((const f32x4*)g)[lane + 64 * i];
;       u32x2 o;
;       o.x = pack2(v[i].x * rs * gg.x, v[i].y * rs * gg.y);
;       o.y = pack2(v[i].z * rs * gg.z, v[i].w * rs * gg.w);
;       *(u32x2*)(H + (size_t)row * 2048 + (size_t)(lane + 64 * i) * 4) = o;
	v_add_f32_e32 v33, v33, v48
	v_fmamk_f32 v33, v33, 0x3a000000, v179
	v_cmp_gt_f32_e32 vcc, s14, v33
	v_mul_f32_e32 v48, 0x4b800000, v33
	s_nop 0
	v_cndmask_b32_e32 v33, v33, v48, vcc
	v_rsq_f32_e32 v33, v33
	s_nop 0
	v_mul_f32_e32 v48, 0x45800000, v33
	v_cndmask_b32_e32 v52, v33, v48, vcc
	v_mov_b64_e32 v[48:49], v[68:69]
	v_mov_b64_e32 v[50:51], v[70:71]
	v_pk_mul_f32 v[0:1], v[2:3], v[52:53] op_sel_hi:[1,0]
	v_pk_mul_f32 v[54:55], v[54:55], v[52:53] op_sel_hi:[1,0]
	v_cmp_lt_i32_e32 vcc, s71, v32
	s_or_b64 s[12:13], vcc, s[12:13]
	v_mov_b32_e32 v57, v50
	v_mov_b32_e32 v50, v49
	v_mov_b32_e32 v56, v48
	v_pk_mul_f32 v[0:1], v[50:51], v[0:1]
	v_pk_mul_f32 v[54:55], v[56:57], v[54:55]
	v_and_b32_sdwa v33, v1, v182 dst_sel:DWORD dst_unused:UNUSED_PAD src0_sel:WORD_1 src1_sel:DWORD
	v_and_b32_sdwa v48, v0, v182 dst_sel:DWORD dst_unused:UNUSED_PAD src0_sel:WORD_1 src1_sel:DWORD
	v_and_b32_sdwa v2, v55, v182 dst_sel:DWORD dst_unused:UNUSED_PAD src0_sel:WORD_1 src1_sel:DWORD
	v_and_b32_sdwa v3, v54, v182 dst_sel:DWORD dst_unused:UNUSED_PAD src0_sel:WORD_1 src1_sel:DWORD
	v_add3_u32 v1, v1, v33, s71
	v_add3_u32 v0, v0, v48, s71
	v_add3_u32 v3, v54, v3, s71
	v_add3_u32 v2, v55, v2, s71
	v_and_b32_e32 v1, 0xffff0000, v1
	v_and_b32_e32 v0, 0xffff0000, v0
	v_or_b32_sdwa v1, v1, v2 dst_sel:DWORD dst_unused:UNUSED_PAD src0_sel:DWORD src1_sel:WORD_1
	v_or_b32_sdwa v0, v0, v3 dst_sel:DWORD dst_unused:UNUSED_PAD src0_sel:DWORD src1_sel:WORD_1
	global_store_dwordx2 v[44:45], v[0:1], off
	v_mov_b64_e32 v[0:1], v[72:73]
	v_mov_b64_e32 v[2:3], v[74:75]
	v_mov_b32_e32 v49, v10
	v_mov_b32_e32 v10, v9
	v_mov_b32_e32 v48, v8
	v_pk_mul_f32 v[8:9], v[10:11], v[52:53] op_sel_hi:[1,0]
	v_pk_mul_f32 v[48:49], v[48:49], v[52:53] op_sel_hi:[1,0]
	v_mov_b32_e32 v51, v2
	v_mov_b32_e32 v2, v1
	v_mov_b32_e32 v50, v0
	v_pk_mul_f32 v[0:1], v[2:3], v[8:9]
	v_pk_mul_f32 v[48:49], v[50:51], v[48:49]
	v_and_b32_sdwa v8, v1, v182 dst_sel:DWORD dst_unused:UNUSED_PAD src0_sel:WORD_1 src1_sel:DWORD
	v_and_b32_sdwa v9, v0, v182 dst_sel:DWORD dst_unused:UNUSED_PAD src0_sel:WORD_1 src1_sel:DWORD
	v_and_b32_sdwa v2, v49, v182 dst_sel:DWORD dst_unused:UNUSED_PAD src0_sel:WORD_1 src1_sel:DWORD
	v_and_b32_sdwa v3, v48, v182 dst_sel:DWORD dst_unused:UNUSED_PAD src0_sel:WORD_1 src1_sel:DWORD
	v_add3_u32 v1, v1, v8, s71
	v_add3_u32 v0, v0, v9, s71
	v_add3_u32 v3, v48, v3, s71
	v_add3_u32 v2, v49, v2, s71
	v_and_b32_e32 v1, 0xffff0000, v1
	v_and_b32_e32 v0, 0xffff0000, v0
	v_or_b32_sdwa v1, v1, v2 dst_sel:DWORD dst_unused:UNUSED_PAD src0_sel:DWORD src1_sel:WORD_1
	v_or_b32_sdwa v0, v0, v3 dst_sel:DWORD dst_unused:UNUSED_PAD src0_sel:DWORD src1_sel:WORD_1
	global_store_dwordx2 v[44:45], v[0:1], off offset:512
	v_mov_b64_e32 v[0:1], v[76:77]
	v_mov_b64_e32 v[2:3], v[78:79]
	v_mov_b32_e32 v8, v12
	v_mov_b32_e32 v9, v14
	v_pk_mul_f32 v[8:9], v[8:9], v[52:53] op_sel_hi:[1,0]
	v_mov_b32_e32 v14, v13
	v_mov_b32_e32 v10, v0
	v_mov_b32_e32 v11, v2
	v_pk_mul_f32 v[8:9], v[10:11], v[8:9]
	v_pk_mul_f32 v[10:11], v[14:15], v[52:53] op_sel_hi:[1,0]
	v_mov_b32_e32 v2, v1
	v_pk_mul_f32 v[0:1], v[2:3], v[10:11]
	v_and_b32_sdwa v2, v9, v182 dst_sel:DWORD dst_unused:UNUSED_PAD src0_sel:WORD_1 src1_sel:DWORD
	v_and_b32_sdwa v3, v8, v182 dst_sel:DWORD dst_unused:UNUSED_PAD src0_sel:WORD_1 src1_sel:DWORD
	v_add3_u32 v3, v8, v3, s71
	v_add3_u32 v2, v9, v2, s71
	v_and_b32_sdwa v8, v1, v182 dst_sel:DWORD dst_unused:UNUSED_PAD src0_sel:WORD_1 src1_sel:DWORD
	v_and_b32_sdwa v9, v0, v182 dst_sel:DWORD dst_unused:UNUSED_PAD src0_sel:WORD_1 src1_sel:DWORD
	v_add3_u32 v1, v1, v8, s71
	v_add3_u32 v0, v0, v9, s71
	v_and_b32_e32 v1, 0xffff0000, v1
	v_and_b32_e32 v0, 0xffff0000, v0
	v_or_b32_sdwa v1, v1, v2 dst_sel:DWORD dst_unused:UNUSED_PAD src0_sel:DWORD src1_sel:WORD_1
	v_or_b32_sdwa v0, v0, v3 dst_sel:DWORD dst_unused:UNUSED_PAD src0_sel:DWORD src1_sel:WORD_1
	global_store_dwordx2 v[44:45], v[0:1], off offset:1024
	v_mov_b64_e32 v[0:1], v[80:81]
	v_mov_b64_e32 v[2:3], v[82:83]
	v_mov_b32_e32 v8, v16
	v_mov_b32_e32 v9, v18
	v_pk_mul_f32 v[8:9], v[8:9], v[52:53] op_sel_hi:[1,0]
	v_mov_b32_e32 v18, v17
	v_mov_b32_e32 v10, v0
	v_mov_b32_e32 v11, v2
	v_pk_mul_f32 v[8:9], v[10:11], v[8:9]
	v_pk_mul_f32 v[10:11], v[18:19], v[52:53] op_sel_hi:[1,0]
	v_mov_b32_e32 v2, v1
	v_pk_mul_f32 v[0:1], v[2:3], v[10:11]
	v_and_b32_sdwa v2, v9, v182 dst_sel:DWORD dst_unused:UNUSED_PAD src0_sel:WORD_1 src1_sel:DWORD
	v_and_b32_sdwa v3, v8, v182 dst_sel:DWORD dst_unused:UNUSED_PAD src0_sel:WORD_1 src1_sel:DWORD
	v_add3_u32 v3, v8, v3, s71
	v_add3_u32 v2, v9, v2, s71
	v_and_b32_sdwa v8, v1, v182 dst_sel:DWORD dst_unused:UNUSED_PAD src0_sel:WORD_1 src1_sel:DWORD
	v_and_b32_sdwa v9, v0, v182 dst_sel:DWORD dst_unused:UNUSED_PAD src0_sel:WORD_1 src1_sel:DWORD
	v_add3_u32 v1, v1, v8, s71
	v_add3_u32 v0, v0, v9, s71
	v_and_b32_e32 v1, 0xffff0000, v1
	v_and_b32_e32 v0, 0xffff0000, v0
	v_or_b32_sdwa v1, v1, v2 dst_sel:DWORD dst_unused:UNUSED_PAD src0_sel:DWORD src1_sel:WORD_1
	v_or_b32_sdwa v0, v0, v3 dst_sel:DWORD dst_unused:UNUSED_PAD src0_sel:DWORD src1_sel:WORD_1
; DEV unsigned pack2(float a, float b) { return (unsigned)f2bf(a) | ((unsigned)f2bf(b) << 16); }
; PHASE void norm_phase(const float* __restrict__ x, const float* __restrict__ g, u16* __restrict__ H) {
;     ...
;     for (int i = 0; i < 8; ++i) {
;       f32x4 gg = ((const f32x4*)g)[lane + 64 * i];
;       u32x2 o;
;       o.x = pack2(v[i].x * rs * gg.x, v[i].y * rs * gg.y);
;       o.y = pack2(v[i].z * rs * gg.z, v[i].w * rs * gg.w);
;       *(u32x2*)(H + (size_t)row * 2048 + (size_t)(lane + 64 * i) * 4) = o;
;     }
;   }
	global_store_dwordx2 v[44:45], v[0:1], off offset:1536
	v_mov_b64_e32 v[0:1], v[84:85]
	v_mov_b64_e32 v[2:3], v[86:87]
	v_mov_b32_e32 v8, v20
	v_mov_b32_e32 v9, v22
	v_pk_mul_f32 v[8:9], v[8:9], v[52:53] op_sel_hi:[1,0]
	v_mov_b32_e32 v22, v21
	v_mov_b32_e32 v10, v0
	v_mov_b32_e32 v11, v2
	v_pk_mul_f32 v[8:9], v[8:9], v[10:11]
	v_pk_mul_f32 v[10:11], v[22:23], v[52:53] op_sel_hi:[1,0]
	v_mov_b32_e32 v2, v1
	v_pk_mul_f32 v[0:1], v[10:11], v[2:3]
	v_and_b32_sdwa v2, v9, v182 dst_sel:DWORD dst_unused:UNUSED_PAD src0_sel:WORD_1 src1_sel:DWORD
	v_and_b32_sdwa v3, v8, v182 dst_sel:DWORD dst_unused:UNUSED_PAD src0_sel:WORD_1 src1_sel:DWORD
	v_add3_u32 v3, v8, v3, s71
	v_add3_u32 v2, v9, v2, s71
	v_and_b32_sdwa v8, v1, v182 dst_sel:DWORD dst_unused:UNUSED_PAD src0_sel:WORD_1 src1_sel:DWORD
	v_and_b32_sdwa v9, v0, v182 dst_sel:DWORD dst_unused:UNUSED_PAD src0_sel:WORD_1 src1_sel:DWORD
	v_add3_u32 v1, v1, v8, s71
	v_add3_u32 v0, v0, v9, s71
	v_and_b32_e32 v1, 0xffff0000, v1
	v_and_b32_e32 v0, 0xffff0000, v0
	v_or_b32_sdwa v1, v1, v2 dst_sel:DWORD dst_unused:UNUSED_PAD src0_sel:DWORD src1_sel:WORD_1
	v_or_b32_sdwa v0, v0, v3 dst_sel:DWORD dst_unused:UNUSED_PAD src0_sel:DWORD src1_sel:WORD_1
	global_store_dwordx2 v[44:45], v[0:1], off offset:2048
	v_mov_b64_e32 v[0:1], v[88:89]
	v_mov_b64_e32 v[2:3], v[90:91]
	v_mov_b32_e32 v9, v6
	v_mov_b32_e32 v6, v5
	v_mov_b32_e32 v8, v4
	v_pk_mul_f32 v[4:5], v[6:7], v[52:53] op_sel_hi:[1,0]
	v_pk_mul_f32 v[8:9], v[8:9], v[52:53] op_sel_hi:[1,0]
	v_mov_b32_e32 v11, v2
	v_mov_b32_e32 v2, v1
	v_mov_b32_e32 v10, v0
	v_pk_mul_f32 v[0:1], v[4:5], v[2:3]
	v_pk_mul_f32 v[8:9], v[8:9], v[10:11]
	v_and_b32_sdwa v4, v1, v182 dst_sel:DWORD dst_unused:UNUSED_PAD src0_sel:WORD_1 src1_sel:DWORD
	v_and_b32_sdwa v5, v0, v182 dst_sel:DWORD dst_unused:UNUSED_PAD src0_sel:WORD_1 src1_sel:DWORD
	v_and_b32_sdwa v2, v9, v182 dst_sel:DWORD dst_unused:UNUSED_PAD src0_sel:WORD_1 src1_sel:DWORD
	v_and_b32_sdwa v3, v8, v182 dst_sel:DWORD dst_unused:UNUSED_PAD src0_sel:WORD_1 src1_sel:DWORD
	v_add3_u32 v1, v1, v4, s71
	v_add3_u32 v0, v0, v5, s71
	v_add3_u32 v3, v8, v3, s71
	v_add3_u32 v2, v9, v2, s71
	v_and_b32_e32 v1, 0xffff0000, v1
	v_and_b32_e32 v0, 0xffff0000, v0
	v_or_b32_sdwa v1, v1, v2 dst_sel:DWORD dst_unused:UNUSED_PAD src0_sel:DWORD src1_sel:WORD_1
	v_or_b32_sdwa v0, v0, v3 dst_sel:DWORD dst_unused:UNUSED_PAD src0_sel:DWORD src1_sel:WORD_1
	global_store_dwordx2 v[44:45], v[0:1], off offset:2560
	v_mov_b64_e32 v[0:1], v[92:93]
	v_mov_b64_e32 v[2:3], v[94:95]
	v_mov_b32_e32 v4, v28
	v_mov_b32_e32 v5, v30
	v_pk_mul_f32 v[4:5], v[4:5], v[52:53] op_sel_hi:[1,0]
	v_mov_b32_e32 v30, v29
	v_mov_b32_e32 v6, v0
	v_mov_b32_e32 v7, v2
	v_pk_mul_f32 v[4:5], v[4:5], v[6:7]
	v_pk_mul_f32 v[6:7], v[30:31], v[52:53] op_sel_hi:[1,0]
	v_mov_b32_e32 v2, v1
	v_pk_mul_f32 v[0:1], v[6:7], v[2:3]
	v_and_b32_sdwa v2, v5, v182 dst_sel:DWORD dst_unused:UNUSED_PAD src0_sel:WORD_1 src1_sel:DWORD
	v_and_b32_sdwa v3, v4, v182 dst_sel:DWORD dst_unused:UNUSED_PAD src0_sel:WORD_1 src1_sel:DWORD
	v_add3_u32 v3, v4, v3, s71
	v_add3_u32 v2, v5, v2, s71
	v_and_b32_sdwa v4, v1, v182 dst_sel:DWORD dst_unused:UNUSED_PAD src0_sel:WORD_1 src1_sel:DWORD
	v_and_b32_sdwa v5, v0, v182 dst_sel:DWORD dst_unused:UNUSED_PAD src0_sel:WORD_1 src1_sel:DWORD
	v_add3_u32 v1, v1, v4, s71
	v_add3_u32 v0, v0, v5, s71
	v_and_b32_e32 v1, 0xffff0000, v1
	v_and_b32_e32 v0, 0xffff0000, v0
	v_or_b32_sdwa v1, v1, v2 dst_sel:DWORD dst_unused:UNUSED_PAD src0_sel:DWORD src1_sel:WORD_1
	v_or_b32_sdwa v0, v0, v3 dst_sel:DWORD dst_unused:UNUSED_PAD src0_sel:DWORD src1_sel:WORD_1
	global_store_dwordx2 v[44:45], v[0:1], off offset:3072
	v_mov_b64_e32 v[0:1], v[96:97]
	v_mov_b64_e32 v[2:3], v[98:99]
	v_mov_b32_e32 v4, v24
	v_mov_b32_e32 v5, v26
	v_pk_mul_f32 v[4:5], v[4:5], v[52:53] op_sel_hi:[1,0]
	v_mov_b32_e32 v26, v25
	v_mov_b32_e32 v6, v0
	v_mov_b32_e32 v7, v2
	v_pk_mul_f32 v[4:5], v[4:5], v[6:7]
	v_pk_mul_f32 v[6:7], v[26:27], v[52:53] op_sel_hi:[1,0]
	v_mov_b32_e32 v2, v1
	v_pk_mul_f32 v[0:1], v[6:7], v[2:3]
	v_and_b32_sdwa v2, v5, v182 dst_sel:DWORD dst_unused:UNUSED_PAD src0_sel:WORD_1 src1_sel:DWORD
	v_and_b32_sdwa v3, v4, v182 dst_sel:DWORD dst_unused:UNUSED_PAD src0_sel:WORD_1 src1_sel:DWORD
	v_add3_u32 v3, v4, v3, s71
	v_add3_u32 v2, v5, v2, s71
	v_and_b32_sdwa v4, v1, v182 dst_sel:DWORD dst_unused:UNUSED_PAD src0_sel:WORD_1 src1_sel:DWORD
	v_and_b32_sdwa v5, v0, v182 dst_sel:DWORD dst_unused:UNUSED_PAD src0_sel:WORD_1 src1_sel:DWORD
	v_add3_u32 v1, v1, v4, s71
	v_add3_u32 v0, v0, v5, s71
	v_and_b32_e32 v1, 0xffff0000, v1
	v_and_b32_e32 v0, 0xffff0000, v0
	v_or_b32_sdwa v1, v1, v2 dst_sel:DWORD dst_unused:UNUSED_PAD src0_sel:DWORD src1_sel:WORD_1
	v_or_b32_sdwa v0, v0, v3 dst_sel:DWORD dst_unused:UNUSED_PAD src0_sel:DWORD src1_sel:WORD_1
	global_store_dwordx2 v[44:45], v[0:1], off offset:3584
	v_lshl_add_u64 v[44:45], v[44:45], 0, s[8:9]
	s_andn2_b64 exec, exec, s[12:13]
	s_cbranch_execnz .LBB0_237
	s_branch .LBB0_234

; DEV unsigned pack2(float a, float b) { return (unsigned)f2bf(a) | ((unsigned)f2bf(b) << 16); }
; DEV float lo2f(unsigned v) { return __uint_as_float(v << 16); }
; DEV float hi2f(unsigned v) { return __uint_as_float(v & 0xffff0000u); }
; DEV float gelu_tanh(float x) {
;   float u = 0.7978845608028654f * (x + 0.044715f * x * x * x);
;   return x / (1.f + __expf(-2.f * u));
; }
; PHASE void lru_phase(const Params& p, int layer, const u16* __restrict__ GC, u16* __restrict__ OC, float* __restrict__ LA, ...
;     ...
;     if (pass3) {
;       __syncthreads();
;       const int cp = tid & 63, tg = tid >> 6;
; #pragma unroll
;       for (int i = 0; i < 16; ++i) {
;         const int t = tg * 16 + i;
;         const unsigned yv = *(const unsigned*)(GC + (base + t0 + t) * 4096 + 2048 + ch0 + 2 * cp);
;         const unsigned hv = *(const unsigned*)(sR + t * 128 + 2 * cp);
;         *(unsigned*)(OC + (base + t0 + t) * 2048 + ch0 + 2 * cp) =
;             pack2(lo2f(hv) * gelu_tanh(lo2f(yv)), hi2f(hv) * gelu_tanh(hi2f(yv)));
;       }
.LBB0_397:
	s_or_b32 s20, s20, s31
	v_lshl_add_u64 v[2:3], s[20:21], 0, v[66:67]
	v_readlane_b32 s24, v249, 62
	v_lshlrev_b64 v[4:5], 13, v[2:3]
	v_readlane_b32 s25, v249, 63
	s_lshl_b32 s24, s29, 1
	v_lshl_add_u64 v[4:5], s[68:69], 0, v[4:5]
	v_lshl_add_u64 v[4:5], v[4:5], 0, s[24:25]
	v_lshlrev_b32_e32 v156, 1, v64
	v_lshl_add_u64 v[4:5], v[4:5], 0, v[156:157]
	v_add_co_u32_e32 v4, vcc, s33, v4
	s_waitcnt lgkmcnt(0)
	s_nop 0
	v_addc_co_u32_e32 v5, vcc, 0, v5, vcc
	s_barrier
	v_mov_b32_e32 v208, 0x2000
	v_mov_b32_e32 v209, 0
	v_mov_b64_e32 v[210:211], v[4:5]
	v_lshl_add_u64 v[210:211], v[210:211], 0, v[208:209]
	global_load_dword v213, v[210:211], off
	v_lshl_add_u64 v[210:211], v[210:211], 0, v[208:209]
	global_load_dword v214, v[210:211], off
	v_lshl_add_u64 v[210:211], v[210:211], 0, v[208:209]
	global_load_dword v215, v[210:211], off
	v_lshl_add_u64 v[210:211], v[210:211], 0, v[208:209]
	global_load_dword v216, v[210:211], off
	v_lshl_add_u64 v[210:211], v[210:211], 0, v[208:209]
	global_load_dword v217, v[210:211], off
	v_lshl_add_u64 v[210:211], v[210:211], 0, v[208:209]
	global_load_dword v218, v[210:211], off
	v_lshl_add_u64 v[210:211], v[210:211], 0, v[208:209]
	global_load_dword v219, v[210:211], off
	v_lshl_add_u64 v[210:211], v[210:211], 0, v[208:209]
	global_load_dword v220, v[210:211], off
	v_lshl_add_u64 v[210:211], v[210:211], 0, v[208:209]
	global_load_dword v221, v[210:211], off
	v_lshl_add_u64 v[210:211], v[210:211], 0, v[208:209]
	global_load_dword v222, v[210:211], off
	v_lshl_add_u64 v[210:211], v[210:211], 0, v[208:209]
	global_load_dword v223, v[210:211], off
	v_lshl_add_u64 v[210:211], v[210:211], 0, v[208:209]
	global_load_dword v224, v[210:211], off
	v_lshl_add_u64 v[210:211], v[210:211], 0, v[208:209]
	global_load_dword v225, v[210:211], off
	v_lshl_add_u64 v[210:211], v[210:211], 0, v[208:209]
	global_load_dword v226, v[210:211], off
	v_lshl_add_u64 v[210:211], v[210:211], 0, v[208:209]
	global_load_dword v227, v[210:211], off
	global_load_dword v4, v[4:5], off
	ds_read_b32 v5, v138 offset:17408
	v_lshl_add_u64 v[0:1], v[72:73], 0, s[24:25]
	v_lshlrev_b64 v[2:3], 12, v[2:3]
	v_lshl_add_u64 v[2:3], v[0:1], 0, v[2:3]
	s_waitcnt lgkmcnt(0)
	v_lshlrev_b32_e32 v6, 16, v5
	v_and_b32_e32 v5, 0xffff0000, v5
	s_waitcnt vmcnt(0)
	v_lshlrev_b32_e32 v7, 16, v4
	v_mul_f32_e32 v8, 0x3d372713, v7
	v_mul_f32_e32 v8, v8, v7
	v_fma_f32 v8, v8, v7, v7
	v_mul_f32_e32 v8, 0x3f4c422a, v8
	v_mul_f32_e32 v8, -2.0, v8
	v_mul_f32_e32 v8, 0x3fb8aa3b, v8
	v_exp_f32_e32 v8, v8
	v_and_b32_e32 v4, 0xffff0000, v4
	v_add_f32_e32 v8, 1.0, v8
	v_div_scale_f32 v9, s[22:23], v8, v8, v7
	v_rcp_f32_e32 v10, v9
	s_nop 0
	v_fma_f32 v11, -v9, v10, 1.0
	v_fmac_f32_e32 v10, v11, v10
	v_div_scale_f32 v11, vcc, v7, v8, v7
	v_mul_f32_e32 v12, v11, v10
	v_fma_f32 v13, -v9, v12, v11
	v_fmac_f32_e32 v12, v13, v10
	v_fma_f32 v9, -v9, v12, v11
	v_div_fmas_f32 v9, v9, v10, v12
	v_div_fixup_f32 v7, v9, v8, v7
	v_mul_f32_e32 v6, v7, v6
	v_mul_f32_e32 v7, 0x3d372713, v4
	v_mul_f32_e32 v7, v7, v4
	v_fma_f32 v7, v7, v4, v4
	v_mul_f32_e32 v7, 0x3f4c422a, v7
	v_mul_f32_e32 v7, -2.0, v7
	v_mul_f32_e32 v7, 0x3fb8aa3b, v7
	v_exp_f32_e32 v7, v7
	s_nop 0
	v_add_f32_e32 v7, 1.0, v7
	v_div_scale_f32 v8, s[22:23], v7, v7, v4
	v_rcp_f32_e32 v9, v8
	s_nop 0
	v_fma_f32 v10, -v8, v9, 1.0
	v_fmac_f32_e32 v9, v10, v9
	v_div_scale_f32 v10, vcc, v4, v7, v4
	v_mul_f32_e32 v11, v10, v9
	v_fma_f32 v12, -v8, v11, v10
	v_fmac_f32_e32 v11, v12, v9
	v_fma_f32 v8, -v8, v11, v10
	v_div_fmas_f32 v8, v8, v9, v11
	v_div_fixup_f32 v4, v8, v7, v4
	v_mul_f32_e32 v4, v4, v5
	v_bfe_u32 v5, v6, 16, 1
	v_add3_u32 v5, v6, v5, s71
	v_bfe_u32 v6, v4, 16, 1
	v_lshrrev_b32_e32 v5, 16, v5
	v_add3_u32 v4, v4, v6, s71
	v_and_or_b32 v4, v4, s81, v5
	global_store_dword v[2:3], v4, off
	v_lshl_add_u64 v[2:3], s[20:21], 0, v[74:75]
	v_lshlrev_b64 v[4:5], 13, v[2:3]
	v_lshl_add_u64 v[4:5], s[68:69], 0, v[4:5]
	v_lshl_add_u64 v[4:5], v[4:5], 0, s[24:25]
	v_lshl_add_u64 v[4:5], v[4:5], 0, v[156:157]
	v_add_co_u32_e32 v4, vcc, s33, v4
	v_lshlrev_b64 v[2:3], 12, v[2:3]
	s_nop 0
	v_addc_co_u32_e32 v5, vcc, 0, v5, vcc
	v_mov_b32_e32 v4, v213
	ds_read_b32 v5, v139 offset:17408
	v_lshl_add_u64 v[2:3], v[0:1], 0, v[2:3]
	s_waitcnt lgkmcnt(0)
	v_lshlrev_b32_e32 v6, 16, v5
	v_and_b32_e32 v5, 0xffff0000, v5
	v_lshlrev_b32_e32 v7, 16, v4
	v_mul_f32_e32 v8, 0x3d372713, v7
	v_mul_f32_e32 v8, v8, v7
	v_fma_f32 v8, v8, v7, v7
	v_mul_f32_e32 v8, 0x3f4c422a, v8
	v_mul_f32_e32 v8, -2.0, v8
	v_mul_f32_e32 v8, 0x3fb8aa3b, v8
	v_exp_f32_e32 v8, v8
	v_and_b32_e32 v4, 0xffff0000, v4
	v_add_f32_e32 v8, 1.0, v8
	v_div_scale_f32 v9, s[22:23], v8, v8, v7
	v_rcp_f32_e32 v10, v9
	s_nop 0
	v_fma_f32 v11, -v9, v10, 1.0
	v_fmac_f32_e32 v10, v11, v10
	v_div_scale_f32 v11, vcc, v7, v8, v7
	v_mul_f32_e32 v12, v11, v10
	v_fma_f32 v13, -v9, v12, v11
	v_fmac_f32_e32 v12, v13, v10
	v_fma_f32 v9, -v9, v12, v11
	v_div_fmas_f32 v9, v9, v10, v12
	v_div_fixup_f32 v7, v9, v8, v7
	v_mul_f32_e32 v6, v7, v6
	v_mul_f32_e32 v7, 0x3d372713, v4
	v_mul_f32_e32 v7, v7, v4
	v_fma_f32 v7, v7, v4, v4
	v_mul_f32_e32 v7, 0x3f4c422a, v7
	v_mul_f32_e32 v7, -2.0, v7
	v_mul_f32_e32 v7, 0x3fb8aa3b, v7
	v_exp_f32_e32 v7, v7
	s_nop 0
	v_add_f32_e32 v7, 1.0, v7
	v_div_scale_f32 v8, s[22:23], v7, v7, v4
	v_rcp_f32_e32 v9, v8
	s_nop 0
	v_fma_f32 v10, -v8, v9, 1.0
	v_fmac_f32_e32 v9, v10, v9
	v_div_scale_f32 v10, vcc, v4, v7, v4
	v_mul_f32_e32 v11, v10, v9
	v_fma_f32 v12, -v8, v11, v10
	v_fmac_f32_e32 v11, v12, v9
	v_fma_f32 v8, -v8, v11, v10
	v_div_fmas_f32 v8, v8, v9, v11
	v_div_fixup_f32 v4, v8, v7, v4
	v_mul_f32_e32 v4, v4, v5
	v_bfe_u32 v5, v6, 16, 1
	v_add3_u32 v5, v6, v5, s71
	v_bfe_u32 v6, v4, 16, 1
	v_lshrrev_b32_e32 v5, 16, v5
	v_add3_u32 v4, v4, v6, s71
	v_and_or_b32 v4, v4, s81, v5
	global_store_dword v[2:3], v4, off
	v_lshl_add_u64 v[2:3], s[20:21], 0, v[76:77]
	v_lshlrev_b64 v[4:5], 13, v[2:3]
	v_lshl_add_u64 v[4:5], s[68:69], 0, v[4:5]
	v_lshl_add_u64 v[4:5], v[4:5], 0, s[24:25]
	v_lshl_add_u64 v[4:5], v[4:5], 0, v[156:157]
	v_add_co_u32_e32 v4, vcc, s33, v4
	v_lshlrev_b64 v[2:3], 12, v[2:3]
	s_nop 0
	v_addc_co_u32_e32 v5, vcc, 0, v5, vcc
	v_mov_b32_e32 v4, v214
	ds_read_b32 v5, v140 offset:17408
	v_lshl_add_u64 v[2:3], v[0:1], 0, v[2:3]
	s_waitcnt lgkmcnt(0)
; DEV unsigned pack2(float a, float b) { return (unsigned)f2bf(a) | ((unsigned)f2bf(b) << 16); }
; DEV float lo2f(unsigned v) { return __uint_as_float(v << 16); }
; DEV float hi2f(unsigned v) { return __uint_as_float(v & 0xffff0000u); }
; DEV float gelu_tanh(float x) {
;   float u = 0.7978845608028654f * (x + 0.044715f * x * x * x);
;   return x / (1.f + __expf(-2.f * u));
; }
; PHASE void lru_phase(const Params& p, int layer, const u16* __restrict__ GC, u16* __restrict__ OC, float* __restrict__ LA, ...
;     ...
; #pragma unroll
;       for (int i = 0; i < 16; ++i) {
;         const int t = tg * 16 + i;
;         const unsigned yv = *(const unsigned*)(GC + (base + t0 + t) * 4096 + 2048 + ch0 + 2 * cp);
;         const unsigned hv = *(const unsigned*)(sR + t * 128 + 2 * cp);
;         *(unsigned*)(OC + (base + t0 + t) * 2048 + ch0 + 2 * cp) =
;             pack2(lo2f(hv) * gelu_tanh(lo2f(yv)), hi2f(hv) * gelu_tanh(hi2f(yv)));
;       }
	v_lshlrev_b32_e32 v6, 16, v5
	v_and_b32_e32 v5, 0xffff0000, v5
	v_lshlrev_b32_e32 v7, 16, v4
	v_mul_f32_e32 v8, 0x3d372713, v7
	v_mul_f32_e32 v8, v8, v7
	v_fma_f32 v8, v8, v7, v7
	v_mul_f32_e32 v8, 0x3f4c422a, v8
	v_mul_f32_e32 v8, -2.0, v8
	v_mul_f32_e32 v8, 0x3fb8aa3b, v8
	v_exp_f32_e32 v8, v8
	v_and_b32_e32 v4, 0xffff0000, v4
	v_add_f32_e32 v8, 1.0, v8
	v_div_scale_f32 v9, s[22:23], v8, v8, v7
	v_rcp_f32_e32 v10, v9
	s_nop 0
	v_fma_f32 v11, -v9, v10, 1.0
	v_fmac_f32_e32 v10, v11, v10
	v_div_scale_f32 v11, vcc, v7, v8, v7
	v_mul_f32_e32 v12, v11, v10
	v_fma_f32 v13, -v9, v12, v11
	v_fmac_f32_e32 v12, v13, v10
	v_fma_f32 v9, -v9, v12, v11
	v_div_fmas_f32 v9, v9, v10, v12
	v_div_fixup_f32 v7, v9, v8, v7
	v_mul_f32_e32 v6, v7, v6
	v_mul_f32_e32 v7, 0x3d372713, v4
	v_mul_f32_e32 v7, v7, v4
	v_fma_f32 v7, v7, v4, v4
	v_mul_f32_e32 v7, 0x3f4c422a, v7
	v_mul_f32_e32 v7, -2.0, v7
	v_mul_f32_e32 v7, 0x3fb8aa3b, v7
	v_exp_f32_e32 v7, v7
	s_nop 0
	v_add_f32_e32 v7, 1.0, v7
	v_div_scale_f32 v8, s[22:23], v7, v7, v4
	v_rcp_f32_e32 v9, v8
	s_nop 0
	v_fma_f32 v10, -v8, v9, 1.0
	v_fmac_f32_e32 v9, v10, v9
	v_div_scale_f32 v10, vcc, v4, v7, v4
	v_mul_f32_e32 v11, v10, v9
	v_fma_f32 v12, -v8, v11, v10
	v_fmac_f32_e32 v11, v12, v9
	v_fma_f32 v8, -v8, v11, v10
	v_div_fmas_f32 v8, v8, v9, v11
	v_div_fixup_f32 v4, v8, v7, v4
	v_mul_f32_e32 v4, v4, v5
	v_bfe_u32 v5, v6, 16, 1
	v_add3_u32 v5, v6, v5, s71
	v_bfe_u32 v6, v4, 16, 1
	v_lshrrev_b32_e32 v5, 16, v5
	v_add3_u32 v4, v4, v6, s71
	v_and_or_b32 v4, v4, s81, v5
	global_store_dword v[2:3], v4, off
	v_lshl_add_u64 v[2:3], s[20:21], 0, v[78:79]
	v_lshlrev_b64 v[4:5], 13, v[2:3]
	v_lshl_add_u64 v[4:5], s[68:69], 0, v[4:5]
	v_lshl_add_u64 v[4:5], v[4:5], 0, s[24:25]
	v_lshl_add_u64 v[4:5], v[4:5], 0, v[156:157]
	v_add_co_u32_e32 v4, vcc, s33, v4
	v_lshlrev_b64 v[2:3], 12, v[2:3]
	s_nop 0
	v_addc_co_u32_e32 v5, vcc, 0, v5, vcc
	v_mov_b32_e32 v4, v215
	ds_read_b32 v5, v141 offset:17408
	v_lshl_add_u64 v[2:3], v[0:1], 0, v[2:3]
	s_waitcnt lgkmcnt(0)
	v_lshlrev_b32_e32 v6, 16, v5
	v_and_b32_e32 v5, 0xffff0000, v5
	v_lshlrev_b32_e32 v7, 16, v4
	v_mul_f32_e32 v8, 0x3d372713, v7
	v_mul_f32_e32 v8, v8, v7
	v_fma_f32 v8, v8, v7, v7
	v_mul_f32_e32 v8, 0x3f4c422a, v8
	v_mul_f32_e32 v8, -2.0, v8
	v_mul_f32_e32 v8, 0x3fb8aa3b, v8
	v_exp_f32_e32 v8, v8
	v_and_b32_e32 v4, 0xffff0000, v4
	v_add_f32_e32 v8, 1.0, v8
	v_div_scale_f32 v9, s[22:23], v8, v8, v7
	v_rcp_f32_e32 v10, v9
	s_nop 0
	v_fma_f32 v11, -v9, v10, 1.0
	v_fmac_f32_e32 v10, v11, v10
	v_div_scale_f32 v11, vcc, v7, v8, v7
	v_mul_f32_e32 v12, v11, v10
	v_fma_f32 v13, -v9, v12, v11
	v_fmac_f32_e32 v12, v13, v10
	v_fma_f32 v9, -v9, v12, v11
	v_div_fmas_f32 v9, v9, v10, v12
	v_div_fixup_f32 v7, v9, v8, v7
	v_mul_f32_e32 v6, v7, v6
	v_mul_f32_e32 v7, 0x3d372713, v4
	v_mul_f32_e32 v7, v7, v4
	v_fma_f32 v7, v7, v4, v4
	v_mul_f32_e32 v7, 0x3f4c422a, v7
	v_mul_f32_e32 v7, -2.0, v7
	v_mul_f32_e32 v7, 0x3fb8aa3b, v7
	v_exp_f32_e32 v7, v7
	s_nop 0
	v_add_f32_e32 v7, 1.0, v7
	v_div_scale_f32 v8, s[22:23], v7, v7, v4
	v_rcp_f32_e32 v9, v8
	s_nop 0
	v_fma_f32 v10, -v8, v9, 1.0
	v_fmac_f32_e32 v9, v10, v9
	v_div_scale_f32 v10, vcc, v4, v7, v4
	v_mul_f32_e32 v11, v10, v9
	v_fma_f32 v12, -v8, v11, v10
	v_fmac_f32_e32 v11, v12, v9
	v_fma_f32 v8, -v8, v11, v10
	v_div_fmas_f32 v8, v8, v9, v11
	v_div_fixup_f32 v4, v8, v7, v4
	v_mul_f32_e32 v4, v4, v5
	v_bfe_u32 v5, v6, 16, 1
	v_add3_u32 v5, v6, v5, s71
	v_bfe_u32 v6, v4, 16, 1
	v_lshrrev_b32_e32 v5, 16, v5
	v_add3_u32 v4, v4, v6, s71
	v_and_or_b32 v4, v4, s81, v5
	global_store_dword v[2:3], v4, off
	v_lshl_add_u64 v[2:3], s[20:21], 0, v[80:81]
	v_lshlrev_b64 v[4:5], 13, v[2:3]
	v_lshl_add_u64 v[4:5], s[68:69], 0, v[4:5]
	v_lshl_add_u64 v[4:5], v[4:5], 0, s[24:25]
	v_lshl_add_u64 v[4:5], v[4:5], 0, v[156:157]
	v_add_co_u32_e32 v4, vcc, s33, v4
	v_lshlrev_b64 v[2:3], 12, v[2:3]
	s_nop 0
	v_addc_co_u32_e32 v5, vcc, 0, v5, vcc
	v_mov_b32_e32 v4, v216
	ds_read_b32 v5, v142 offset:17408
	v_lshl_add_u64 v[2:3], v[0:1], 0, v[2:3]
	s_waitcnt lgkmcnt(0)
	v_lshlrev_b32_e32 v6, 16, v5
	v_and_b32_e32 v5, 0xffff0000, v5
	v_lshlrev_b32_e32 v7, 16, v4
	v_mul_f32_e32 v8, 0x3d372713, v7
	v_mul_f32_e32 v8, v8, v7
	v_fma_f32 v8, v8, v7, v7
	v_mul_f32_e32 v8, 0x3f4c422a, v8
	v_mul_f32_e32 v8, -2.0, v8
	v_mul_f32_e32 v8, 0x3fb8aa3b, v8
	v_exp_f32_e32 v8, v8
	v_and_b32_e32 v4, 0xffff0000, v4
	v_add_f32_e32 v8, 1.0, v8
	v_div_scale_f32 v9, s[22:23], v8, v8, v7
	v_rcp_f32_e32 v10, v9
	s_nop 0
	v_fma_f32 v11, -v9, v10, 1.0
	v_fmac_f32_e32 v10, v11, v10
	v_div_scale_f32 v11, vcc, v7, v8, v7
	v_mul_f32_e32 v12, v11, v10
	v_fma_f32 v13, -v9, v12, v11
	v_fmac_f32_e32 v12, v13, v10
	v_fma_f32 v9, -v9, v12, v11
	v_div_fmas_f32 v9, v9, v10, v12
	v_div_fixup_f32 v7, v9, v8, v7
	v_mul_f32_e32 v6, v7, v6
	v_mul_f32_e32 v7, 0x3d372713, v4
	v_mul_f32_e32 v7, v7, v4
	v_fma_f32 v7, v7, v4, v4
	v_mul_f32_e32 v7, 0x3f4c422a, v7
	v_mul_f32_e32 v7, -2.0, v7
	v_mul_f32_e32 v7, 0x3fb8aa3b, v7
	v_exp_f32_e32 v7, v7
	s_nop 0
	v_add_f32_e32 v7, 1.0, v7
	v_div_scale_f32 v8, s[22:23], v7, v7, v4
	v_rcp_f32_e32 v9, v8
	s_nop 0
	v_fma_f32 v10, -v8, v9, 1.0
	v_fmac_f32_e32 v9, v10, v9
	v_div_scale_f32 v10, vcc, v4, v7, v4
	v_mul_f32_e32 v11, v10, v9
	v_fma_f32 v12, -v8, v11, v10
	v_fmac_f32_e32 v11, v12, v9
	v_fma_f32 v8, -v8, v11, v10
	v_div_fmas_f32 v8, v8, v9, v11
	v_div_fixup_f32 v4, v8, v7, v4
	v_mul_f32_e32 v4, v4, v5
	v_bfe_u32 v5, v6, 16, 1
	v_add3_u32 v5, v6, v5, s71
	v_bfe_u32 v6, v4, 16, 1
	v_lshrrev_b32_e32 v5, 16, v5
	v_add3_u32 v4, v4, v6, s71
	v_and_or_b32 v4, v4, s81, v5
	global_store_dword v[2:3], v4, off
	v_lshl_add_u64 v[2:3], s[20:21], 0, v[82:83]
	v_lshlrev_b64 v[4:5], 13, v[2:3]
	v_lshl_add_u64 v[4:5], s[68:69], 0, v[4:5]
	v_lshl_add_u64 v[4:5], v[4:5], 0, s[24:25]
	v_lshl_add_u64 v[4:5], v[4:5], 0, v[156:157]
	v_add_co_u32_e32 v4, vcc, s33, v4
	v_lshlrev_b64 v[2:3], 12, v[2:3]
	s_nop 0
	v_addc_co_u32_e32 v5, vcc, 0, v5, vcc
	v_mov_b32_e32 v4, v217
	ds_read_b32 v5, v143 offset:17408
	v_lshl_add_u64 v[2:3], v[0:1], 0, v[2:3]
	s_waitcnt lgkmcnt(0)
; DEV unsigned pack2(float a, float b) { return (unsigned)f2bf(a) | ((unsigned)f2bf(b) << 16); }
; DEV float lo2f(unsigned v) { return __uint_as_float(v << 16); }
; DEV float hi2f(unsigned v) { return __uint_as_float(v & 0xffff0000u); }
; DEV float gelu_tanh(float x) {
;   float u = 0.7978845608028654f * (x + 0.044715f * x * x * x);
;   return x / (1.f + __expf(-2.f * u));
; }
; PHASE void lru_phase(const Params& p, int layer, const u16* __restrict__ GC, u16* __restrict__ OC, float* __restrict__ LA, ...
;     ...
; #pragma unroll
;       for (int i = 0; i < 16; ++i) {
;         const int t = tg * 16 + i;
;         const unsigned yv = *(const unsigned*)(GC + (base + t0 + t) * 4096 + 2048 + ch0 + 2 * cp);
;         const unsigned hv = *(const unsigned*)(sR + t * 128 + 2 * cp);
;         *(unsigned*)(OC + (base + t0 + t) * 2048 + ch0 + 2 * cp) =
;             pack2(lo2f(hv) * gelu_tanh(lo2f(yv)), hi2f(hv) * gelu_tanh(hi2f(yv)));
;       }
	v_lshlrev_b32_e32 v6, 16, v5
	v_and_b32_e32 v5, 0xffff0000, v5
	v_lshlrev_b32_e32 v7, 16, v4
	v_mul_f32_e32 v8, 0x3d372713, v7
	v_mul_f32_e32 v8, v8, v7
	v_fma_f32 v8, v8, v7, v7
	v_mul_f32_e32 v8, 0x3f4c422a, v8
	v_mul_f32_e32 v8, -2.0, v8
	v_mul_f32_e32 v8, 0x3fb8aa3b, v8
	v_exp_f32_e32 v8, v8
	v_and_b32_e32 v4, 0xffff0000, v4
	v_add_f32_e32 v8, 1.0, v8
	v_div_scale_f32 v9, s[22:23], v8, v8, v7
	v_rcp_f32_e32 v10, v9
	s_nop 0
	v_fma_f32 v11, -v9, v10, 1.0
	v_fmac_f32_e32 v10, v11, v10
	v_div_scale_f32 v11, vcc, v7, v8, v7
	v_mul_f32_e32 v12, v11, v10
	v_fma_f32 v13, -v9, v12, v11
	v_fmac_f32_e32 v12, v13, v10
	v_fma_f32 v9, -v9, v12, v11
	v_div_fmas_f32 v9, v9, v10, v12
	v_div_fixup_f32 v7, v9, v8, v7
	v_mul_f32_e32 v6, v7, v6
	v_mul_f32_e32 v7, 0x3d372713, v4
	v_mul_f32_e32 v7, v7, v4
	v_fma_f32 v7, v7, v4, v4
	v_mul_f32_e32 v7, 0x3f4c422a, v7
	v_mul_f32_e32 v7, -2.0, v7
	v_mul_f32_e32 v7, 0x3fb8aa3b, v7
	v_exp_f32_e32 v7, v7
	s_nop 0
	v_add_f32_e32 v7, 1.0, v7
	v_div_scale_f32 v8, s[22:23], v7, v7, v4
	v_rcp_f32_e32 v9, v8
	s_nop 0
	v_fma_f32 v10, -v8, v9, 1.0
	v_fmac_f32_e32 v9, v10, v9
	v_div_scale_f32 v10, vcc, v4, v7, v4
	v_mul_f32_e32 v11, v10, v9
	v_fma_f32 v12, -v8, v11, v10
	v_fmac_f32_e32 v11, v12, v9
	v_fma_f32 v8, -v8, v11, v10
	v_div_fmas_f32 v8, v8, v9, v11
	v_div_fixup_f32 v4, v8, v7, v4
	v_mul_f32_e32 v4, v4, v5
	v_bfe_u32 v5, v6, 16, 1
	v_add3_u32 v5, v6, v5, s71
	v_bfe_u32 v6, v4, 16, 1
	v_lshrrev_b32_e32 v5, 16, v5
	v_add3_u32 v4, v4, v6, s71
	v_and_or_b32 v4, v4, s81, v5
	global_store_dword v[2:3], v4, off
	v_lshl_add_u64 v[2:3], s[20:21], 0, v[84:85]
	v_lshlrev_b64 v[4:5], 13, v[2:3]
	v_lshl_add_u64 v[4:5], s[68:69], 0, v[4:5]
	v_lshl_add_u64 v[4:5], v[4:5], 0, s[24:25]
	v_lshl_add_u64 v[4:5], v[4:5], 0, v[156:157]
	v_add_co_u32_e32 v4, vcc, s33, v4
	v_lshlrev_b64 v[2:3], 12, v[2:3]
	s_nop 0
	v_addc_co_u32_e32 v5, vcc, 0, v5, vcc
	v_mov_b32_e32 v4, v218
	ds_read_b32 v5, v144 offset:17408
	v_lshl_add_u64 v[2:3], v[0:1], 0, v[2:3]
	s_waitcnt lgkmcnt(0)
	v_lshlrev_b32_e32 v6, 16, v5
	v_and_b32_e32 v5, 0xffff0000, v5
	v_lshlrev_b32_e32 v7, 16, v4
	v_mul_f32_e32 v8, 0x3d372713, v7
	v_mul_f32_e32 v8, v8, v7
	v_fma_f32 v8, v8, v7, v7
	v_mul_f32_e32 v8, 0x3f4c422a, v8
	v_mul_f32_e32 v8, -2.0, v8
	v_mul_f32_e32 v8, 0x3fb8aa3b, v8
	v_exp_f32_e32 v8, v8
	v_and_b32_e32 v4, 0xffff0000, v4
	v_add_f32_e32 v8, 1.0, v8
	v_div_scale_f32 v9, s[22:23], v8, v8, v7
	v_rcp_f32_e32 v10, v9
	s_nop 0
	v_fma_f32 v11, -v9, v10, 1.0
	v_fmac_f32_e32 v10, v11, v10
	v_div_scale_f32 v11, vcc, v7, v8, v7
	v_mul_f32_e32 v12, v11, v10
	v_fma_f32 v13, -v9, v12, v11
	v_fmac_f32_e32 v12, v13, v10
	v_fma_f32 v9, -v9, v12, v11
	v_div_fmas_f32 v9, v9, v10, v12
	v_div_fixup_f32 v7, v9, v8, v7
	v_mul_f32_e32 v6, v7, v6
	v_mul_f32_e32 v7, 0x3d372713, v4
	v_mul_f32_e32 v7, v7, v4
	v_fma_f32 v7, v7, v4, v4
	v_mul_f32_e32 v7, 0x3f4c422a, v7
	v_mul_f32_e32 v7, -2.0, v7
	v_mul_f32_e32 v7, 0x3fb8aa3b, v7
	v_exp_f32_e32 v7, v7
	s_nop 0
	v_add_f32_e32 v7, 1.0, v7
	v_div_scale_f32 v8, s[22:23], v7, v7, v4
	v_rcp_f32_e32 v9, v8
	s_nop 0
	v_fma_f32 v10, -v8, v9, 1.0
	v_fmac_f32_e32 v9, v10, v9
	v_div_scale_f32 v10, vcc, v4, v7, v4
	v_mul_f32_e32 v11, v10, v9
	v_fma_f32 v12, -v8, v11, v10
	v_fmac_f32_e32 v11, v12, v9
	v_fma_f32 v8, -v8, v11, v10
	v_div_fmas_f32 v8, v8, v9, v11
	v_div_fixup_f32 v4, v8, v7, v4
	v_mul_f32_e32 v4, v4, v5
	v_bfe_u32 v5, v6, 16, 1
	v_add3_u32 v5, v6, v5, s71
	v_bfe_u32 v6, v4, 16, 1
	v_lshrrev_b32_e32 v5, 16, v5
	v_add3_u32 v4, v4, v6, s71
	v_and_or_b32 v4, v4, s81, v5
	global_store_dword v[2:3], v4, off
	v_lshl_add_u64 v[2:3], s[20:21], 0, v[86:87]
	v_lshlrev_b64 v[4:5], 13, v[2:3]
	v_lshl_add_u64 v[4:5], s[68:69], 0, v[4:5]
	v_lshl_add_u64 v[4:5], v[4:5], 0, s[24:25]
	v_lshl_add_u64 v[4:5], v[4:5], 0, v[156:157]
	v_add_co_u32_e32 v4, vcc, s33, v4
	v_lshlrev_b64 v[2:3], 12, v[2:3]
	s_nop 0
	v_addc_co_u32_e32 v5, vcc, 0, v5, vcc
	v_mov_b32_e32 v4, v219
	ds_read_b32 v5, v145 offset:17408
	v_lshl_add_u64 v[2:3], v[0:1], 0, v[2:3]
	s_waitcnt lgkmcnt(0)
	v_lshlrev_b32_e32 v6, 16, v5
	v_and_b32_e32 v5, 0xffff0000, v5
	v_lshlrev_b32_e32 v7, 16, v4
	v_mul_f32_e32 v8, 0x3d372713, v7
	v_mul_f32_e32 v8, v8, v7
	v_fma_f32 v8, v8, v7, v7
	v_mul_f32_e32 v8, 0x3f4c422a, v8
	v_mul_f32_e32 v8, -2.0, v8
	v_mul_f32_e32 v8, 0x3fb8aa3b, v8
	v_exp_f32_e32 v8, v8
	v_and_b32_e32 v4, 0xffff0000, v4
	v_add_f32_e32 v8, 1.0, v8
	v_div_scale_f32 v9, s[22:23], v8, v8, v7
	v_rcp_f32_e32 v10, v9
	s_nop 0
	v_fma_f32 v11, -v9, v10, 1.0
	v_fmac_f32_e32 v10, v11, v10
	v_div_scale_f32 v11, vcc, v7, v8, v7
	v_mul_f32_e32 v12, v11, v10
	v_fma_f32 v13, -v9, v12, v11
	v_fmac_f32_e32 v12, v13, v10
	v_fma_f32 v9, -v9, v12, v11
	v_div_fmas_f32 v9, v9, v10, v12
	v_div_fixup_f32 v7, v9, v8, v7
	v_mul_f32_e32 v6, v7, v6
	v_mul_f32_e32 v7, 0x3d372713, v4
	v_mul_f32_e32 v7, v7, v4
	v_fma_f32 v7, v7, v4, v4
	v_mul_f32_e32 v7, 0x3f4c422a, v7
	v_mul_f32_e32 v7, -2.0, v7
	v_mul_f32_e32 v7, 0x3fb8aa3b, v7
	v_exp_f32_e32 v7, v7
	s_nop 0
	v_add_f32_e32 v7, 1.0, v7
	v_div_scale_f32 v8, s[22:23], v7, v7, v4
	v_rcp_f32_e32 v9, v8
	s_nop 0
	v_fma_f32 v10, -v8, v9, 1.0
	v_fmac_f32_e32 v9, v10, v9
	v_div_scale_f32 v10, vcc, v4, v7, v4
	v_mul_f32_e32 v11, v10, v9
	v_fma_f32 v12, -v8, v11, v10
	v_fmac_f32_e32 v11, v12, v9
	v_fma_f32 v8, -v8, v11, v10
	v_div_fmas_f32 v8, v8, v9, v11
	v_div_fixup_f32 v4, v8, v7, v4
	v_mul_f32_e32 v4, v4, v5
	v_bfe_u32 v5, v6, 16, 1
	v_add3_u32 v5, v6, v5, s71
	v_bfe_u32 v6, v4, 16, 1
	v_lshrrev_b32_e32 v5, 16, v5
	v_add3_u32 v4, v4, v6, s71
	v_and_or_b32 v4, v4, s81, v5
	global_store_dword v[2:3], v4, off
	v_lshl_add_u64 v[2:3], s[20:21], 0, v[88:89]
	v_lshlrev_b64 v[4:5], 13, v[2:3]
	v_lshl_add_u64 v[4:5], s[68:69], 0, v[4:5]
	v_lshl_add_u64 v[4:5], v[4:5], 0, s[24:25]
	v_lshl_add_u64 v[4:5], v[4:5], 0, v[156:157]
	v_add_co_u32_e32 v4, vcc, s33, v4
	v_lshlrev_b64 v[2:3], 12, v[2:3]
	s_nop 0
	v_addc_co_u32_e32 v5, vcc, 0, v5, vcc
	v_mov_b32_e32 v4, v220
	ds_read_b32 v5, v146 offset:17408
	v_lshl_add_u64 v[2:3], v[0:1], 0, v[2:3]
	s_waitcnt lgkmcnt(0)
; DEV unsigned pack2(float a, float b) { return (unsigned)f2bf(a) | ((unsigned)f2bf(b) << 16); }
; DEV float lo2f(unsigned v) { return __uint_as_float(v << 16); }
; DEV float hi2f(unsigned v) { return __uint_as_float(v & 0xffff0000u); }
; DEV float gelu_tanh(float x) {
;   float u = 0.7978845608028654f * (x + 0.044715f * x * x * x);
;   return x / (1.f + __expf(-2.f * u));
; }
; PHASE void lru_phase(const Params& p, int layer, const u16* __restrict__ GC, u16* __restrict__ OC, float* __restrict__ LA, ...
;     ...
; #pragma unroll
;       for (int i = 0; i < 16; ++i) {
;         const int t = tg * 16 + i;
;         const unsigned yv = *(const unsigned*)(GC + (base + t0 + t) * 4096 + 2048 + ch0 + 2 * cp);
;         const unsigned hv = *(const unsigned*)(sR + t * 128 + 2 * cp);
;         *(unsigned*)(OC + (base + t0 + t) * 2048 + ch0 + 2 * cp) =
;             pack2(lo2f(hv) * gelu_tanh(lo2f(yv)), hi2f(hv) * gelu_tanh(hi2f(yv)));
;       }
	v_lshlrev_b32_e32 v6, 16, v5
	v_and_b32_e32 v5, 0xffff0000, v5
	v_lshlrev_b32_e32 v7, 16, v4
	v_mul_f32_e32 v8, 0x3d372713, v7
	v_mul_f32_e32 v8, v8, v7
	v_fma_f32 v8, v8, v7, v7
	v_mul_f32_e32 v8, 0x3f4c422a, v8
	v_mul_f32_e32 v8, -2.0, v8
	v_mul_f32_e32 v8, 0x3fb8aa3b, v8
	v_exp_f32_e32 v8, v8
	v_and_b32_e32 v4, 0xffff0000, v4
	v_add_f32_e32 v8, 1.0, v8
	v_div_scale_f32 v9, s[22:23], v8, v8, v7
	v_rcp_f32_e32 v10, v9
	s_nop 0
	v_fma_f32 v11, -v9, v10, 1.0
	v_fmac_f32_e32 v10, v11, v10
	v_div_scale_f32 v11, vcc, v7, v8, v7
	v_mul_f32_e32 v12, v11, v10
	v_fma_f32 v13, -v9, v12, v11
	v_fmac_f32_e32 v12, v13, v10
	v_fma_f32 v9, -v9, v12, v11
	v_div_fmas_f32 v9, v9, v10, v12
	v_div_fixup_f32 v7, v9, v8, v7
	v_mul_f32_e32 v6, v7, v6
	v_mul_f32_e32 v7, 0x3d372713, v4
	v_mul_f32_e32 v7, v7, v4
	v_fma_f32 v7, v7, v4, v4
	v_mul_f32_e32 v7, 0x3f4c422a, v7
	v_mul_f32_e32 v7, -2.0, v7
	v_mul_f32_e32 v7, 0x3fb8aa3b, v7
	v_exp_f32_e32 v7, v7
	s_nop 0
	v_add_f32_e32 v7, 1.0, v7
	v_div_scale_f32 v8, s[22:23], v7, v7, v4
	v_rcp_f32_e32 v9, v8
	s_nop 0
	v_fma_f32 v10, -v8, v9, 1.0
	v_fmac_f32_e32 v9, v10, v9
	v_div_scale_f32 v10, vcc, v4, v7, v4
	v_mul_f32_e32 v11, v10, v9
	v_fma_f32 v12, -v8, v11, v10
	v_fmac_f32_e32 v11, v12, v9
	v_fma_f32 v8, -v8, v11, v10
	v_div_fmas_f32 v8, v8, v9, v11
	v_div_fixup_f32 v4, v8, v7, v4
	v_mul_f32_e32 v4, v4, v5
	v_bfe_u32 v5, v6, 16, 1
	v_add3_u32 v5, v6, v5, s71
	v_bfe_u32 v6, v4, 16, 1
	v_lshrrev_b32_e32 v5, 16, v5
	v_add3_u32 v4, v4, v6, s71
	v_and_or_b32 v4, v4, s81, v5
	global_store_dword v[2:3], v4, off
	v_lshl_add_u64 v[2:3], s[20:21], 0, v[90:91]
	v_lshlrev_b64 v[4:5], 13, v[2:3]
	v_lshl_add_u64 v[4:5], s[68:69], 0, v[4:5]
	v_lshl_add_u64 v[4:5], v[4:5], 0, s[24:25]
	v_lshl_add_u64 v[4:5], v[4:5], 0, v[156:157]
	v_add_co_u32_e32 v4, vcc, s33, v4
	v_lshlrev_b64 v[2:3], 12, v[2:3]
	s_nop 0
	v_addc_co_u32_e32 v5, vcc, 0, v5, vcc
	v_mov_b32_e32 v4, v221
	ds_read_b32 v5, v147 offset:17408
	v_lshl_add_u64 v[2:3], v[0:1], 0, v[2:3]
	s_waitcnt lgkmcnt(0)
	v_lshlrev_b32_e32 v6, 16, v5
	v_and_b32_e32 v5, 0xffff0000, v5
	v_lshlrev_b32_e32 v7, 16, v4
	v_mul_f32_e32 v8, 0x3d372713, v7
	v_mul_f32_e32 v8, v8, v7
	v_fma_f32 v8, v8, v7, v7
	v_mul_f32_e32 v8, 0x3f4c422a, v8
	v_mul_f32_e32 v8, -2.0, v8
	v_mul_f32_e32 v8, 0x3fb8aa3b, v8
	v_exp_f32_e32 v8, v8
	v_and_b32_e32 v4, 0xffff0000, v4
	v_add_f32_e32 v8, 1.0, v8
	v_div_scale_f32 v9, s[22:23], v8, v8, v7
	v_rcp_f32_e32 v10, v9
	s_nop 0
	v_fma_f32 v11, -v9, v10, 1.0
	v_fmac_f32_e32 v10, v11, v10
	v_div_scale_f32 v11, vcc, v7, v8, v7
	v_mul_f32_e32 v12, v11, v10
	v_fma_f32 v13, -v9, v12, v11
	v_fmac_f32_e32 v12, v13, v10
	v_fma_f32 v9, -v9, v12, v11
	v_div_fmas_f32 v9, v9, v10, v12
	v_div_fixup_f32 v7, v9, v8, v7
	v_mul_f32_e32 v6, v7, v6
	v_mul_f32_e32 v7, 0x3d372713, v4
	v_mul_f32_e32 v7, v7, v4
	v_fma_f32 v7, v7, v4, v4
	v_mul_f32_e32 v7, 0x3f4c422a, v7
	v_mul_f32_e32 v7, -2.0, v7
	v_mul_f32_e32 v7, 0x3fb8aa3b, v7
	v_exp_f32_e32 v7, v7
	s_nop 0
	v_add_f32_e32 v7, 1.0, v7
	v_div_scale_f32 v8, s[22:23], v7, v7, v4
	v_rcp_f32_e32 v9, v8
	s_nop 0
	v_fma_f32 v10, -v8, v9, 1.0
	v_fmac_f32_e32 v9, v10, v9
	v_div_scale_f32 v10, vcc, v4, v7, v4
	v_mul_f32_e32 v11, v10, v9
	v_fma_f32 v12, -v8, v11, v10
	v_fmac_f32_e32 v11, v12, v9
	v_fma_f32 v8, -v8, v11, v10
	v_div_fmas_f32 v8, v8, v9, v11
	v_div_fixup_f32 v4, v8, v7, v4
	v_mul_f32_e32 v4, v4, v5
	v_bfe_u32 v5, v6, 16, 1
	v_add3_u32 v5, v6, v5, s71
	v_bfe_u32 v6, v4, 16, 1
	v_lshrrev_b32_e32 v5, 16, v5
	v_add3_u32 v4, v4, v6, s71
	v_and_or_b32 v4, v4, s81, v5
	global_store_dword v[2:3], v4, off
	v_lshl_add_u64 v[2:3], s[20:21], 0, v[92:93]
	v_lshlrev_b64 v[4:5], 13, v[2:3]
	v_lshl_add_u64 v[4:5], s[68:69], 0, v[4:5]
	v_lshl_add_u64 v[4:5], v[4:5], 0, s[24:25]
	v_lshl_add_u64 v[4:5], v[4:5], 0, v[156:157]
	v_add_co_u32_e32 v4, vcc, s33, v4
	v_lshlrev_b64 v[2:3], 12, v[2:3]
	s_nop 0
	v_addc_co_u32_e32 v5, vcc, 0, v5, vcc
	v_mov_b32_e32 v4, v222
	ds_read_b32 v5, v148 offset:17408
	v_lshl_add_u64 v[2:3], v[0:1], 0, v[2:3]
	s_waitcnt lgkmcnt(0)
	v_lshlrev_b32_e32 v6, 16, v5
	v_and_b32_e32 v5, 0xffff0000, v5
	v_lshlrev_b32_e32 v7, 16, v4
	v_mul_f32_e32 v8, 0x3d372713, v7
	v_mul_f32_e32 v8, v8, v7
	v_fma_f32 v8, v8, v7, v7
	v_mul_f32_e32 v8, 0x3f4c422a, v8
	v_mul_f32_e32 v8, -2.0, v8
	v_mul_f32_e32 v8, 0x3fb8aa3b, v8
	v_exp_f32_e32 v8, v8
	v_and_b32_e32 v4, 0xffff0000, v4
	v_add_f32_e32 v8, 1.0, v8
	v_div_scale_f32 v9, s[22:23], v8, v8, v7
	v_rcp_f32_e32 v10, v9
	s_nop 0
	v_fma_f32 v11, -v9, v10, 1.0
	v_fmac_f32_e32 v10, v11, v10
	v_div_scale_f32 v11, vcc, v7, v8, v7
	v_mul_f32_e32 v12, v11, v10
	v_fma_f32 v13, -v9, v12, v11
	v_fmac_f32_e32 v12, v13, v10
	v_fma_f32 v9, -v9, v12, v11
	v_div_fmas_f32 v9, v9, v10, v12
	v_div_fixup_f32 v7, v9, v8, v7
	v_mul_f32_e32 v6, v7, v6
	v_mul_f32_e32 v7, 0x3d372713, v4
	v_mul_f32_e32 v7, v7, v4
	v_fma_f32 v7, v7, v4, v4
	v_mul_f32_e32 v7, 0x3f4c422a, v7
	v_mul_f32_e32 v7, -2.0, v7
	v_mul_f32_e32 v7, 0x3fb8aa3b, v7
	v_exp_f32_e32 v7, v7
	s_nop 0
	v_add_f32_e32 v7, 1.0, v7
	v_div_scale_f32 v8, s[22:23], v7, v7, v4
	v_rcp_f32_e32 v9, v8
	s_nop 0
	v_fma_f32 v10, -v8, v9, 1.0
	v_fmac_f32_e32 v9, v10, v9
	v_div_scale_f32 v10, vcc, v4, v7, v4
	v_mul_f32_e32 v11, v10, v9
	v_fma_f32 v12, -v8, v11, v10
	v_fmac_f32_e32 v11, v12, v9
	v_fma_f32 v8, -v8, v11, v10
	v_div_fmas_f32 v8, v8, v9, v11
	v_div_fixup_f32 v4, v8, v7, v4
	v_mul_f32_e32 v4, v4, v5
	v_bfe_u32 v5, v6, 16, 1
	v_add3_u32 v5, v6, v5, s71
	v_bfe_u32 v6, v4, 16, 1
	v_lshrrev_b32_e32 v5, 16, v5
	v_add3_u32 v4, v4, v6, s71
	v_and_or_b32 v4, v4, s81, v5
	global_store_dword v[2:3], v4, off
	v_lshl_add_u64 v[2:3], s[20:21], 0, v[94:95]
	v_lshlrev_b64 v[4:5], 13, v[2:3]
	v_lshl_add_u64 v[4:5], s[68:69], 0, v[4:5]
	v_lshl_add_u64 v[4:5], v[4:5], 0, s[24:25]
	v_lshl_add_u64 v[4:5], v[4:5], 0, v[156:157]
	v_add_co_u32_e32 v4, vcc, s33, v4
	v_lshlrev_b64 v[2:3], 12, v[2:3]
	s_nop 0
	v_addc_co_u32_e32 v5, vcc, 0, v5, vcc
	v_mov_b32_e32 v4, v223
	ds_read_b32 v5, v149 offset:17408
	v_lshl_add_u64 v[2:3], v[0:1], 0, v[2:3]
	s_waitcnt lgkmcnt(0)
; DEV unsigned pack2(float a, float b) { return (unsigned)f2bf(a) | ((unsigned)f2bf(b) << 16); }
; DEV float lo2f(unsigned v) { return __uint_as_float(v << 16); }
; DEV float hi2f(unsigned v) { return __uint_as_float(v & 0xffff0000u); }
; DEV float gelu_tanh(float x) {
;   float u = 0.7978845608028654f * (x + 0.044715f * x * x * x);
;   return x / (1.f + __expf(-2.f * u));
; }
; PHASE void lru_phase(const Params& p, int layer, const u16* __restrict__ GC, u16* __restrict__ OC, float* __restrict__ LA, ...
;     ...
; #pragma unroll
;       for (int i = 0; i < 16; ++i) {
;         const int t = tg * 16 + i;
;         const unsigned yv = *(const unsigned*)(GC + (base + t0 + t) * 4096 + 2048 + ch0 + 2 * cp);
;         const unsigned hv = *(const unsigned*)(sR + t * 128 + 2 * cp);
;         *(unsigned*)(OC + (base + t0 + t) * 2048 + ch0 + 2 * cp) =
;             pack2(lo2f(hv) * gelu_tanh(lo2f(yv)), hi2f(hv) * gelu_tanh(hi2f(yv)));
;       }
	v_lshlrev_b32_e32 v6, 16, v5
	v_and_b32_e32 v5, 0xffff0000, v5
	v_lshlrev_b32_e32 v7, 16, v4
	v_mul_f32_e32 v8, 0x3d372713, v7
	v_mul_f32_e32 v8, v8, v7
	v_fma_f32 v8, v8, v7, v7
	v_mul_f32_e32 v8, 0x3f4c422a, v8
	v_mul_f32_e32 v8, -2.0, v8
	v_mul_f32_e32 v8, 0x3fb8aa3b, v8
	v_exp_f32_e32 v8, v8
	v_and_b32_e32 v4, 0xffff0000, v4
	v_add_f32_e32 v8, 1.0, v8
	v_div_scale_f32 v9, s[22:23], v8, v8, v7
	v_rcp_f32_e32 v10, v9
	s_nop 0
	v_fma_f32 v11, -v9, v10, 1.0
	v_fmac_f32_e32 v10, v11, v10
	v_div_scale_f32 v11, vcc, v7, v8, v7
	v_mul_f32_e32 v12, v11, v10
	v_fma_f32 v13, -v9, v12, v11
	v_fmac_f32_e32 v12, v13, v10
	v_fma_f32 v9, -v9, v12, v11
	v_div_fmas_f32 v9, v9, v10, v12
	v_div_fixup_f32 v7, v9, v8, v7
	v_mul_f32_e32 v6, v7, v6
	v_mul_f32_e32 v7, 0x3d372713, v4
	v_mul_f32_e32 v7, v7, v4
	v_fma_f32 v7, v7, v4, v4
	v_mul_f32_e32 v7, 0x3f4c422a, v7
	v_mul_f32_e32 v7, -2.0, v7
	v_mul_f32_e32 v7, 0x3fb8aa3b, v7
	v_exp_f32_e32 v7, v7
	s_nop 0
	v_add_f32_e32 v7, 1.0, v7
	v_div_scale_f32 v8, s[22:23], v7, v7, v4
	v_rcp_f32_e32 v9, v8
	s_nop 0
	v_fma_f32 v10, -v8, v9, 1.0
	v_fmac_f32_e32 v9, v10, v9
	v_div_scale_f32 v10, vcc, v4, v7, v4
	v_mul_f32_e32 v11, v10, v9
	v_fma_f32 v12, -v8, v11, v10
	v_fmac_f32_e32 v11, v12, v9
	v_fma_f32 v8, -v8, v11, v10
	v_div_fmas_f32 v8, v8, v9, v11
	v_div_fixup_f32 v4, v8, v7, v4
	v_mul_f32_e32 v4, v4, v5
	v_bfe_u32 v5, v6, 16, 1
	v_add3_u32 v5, v6, v5, s71
	v_bfe_u32 v6, v4, 16, 1
	v_lshrrev_b32_e32 v5, 16, v5
	v_add3_u32 v4, v4, v6, s71
	v_and_or_b32 v4, v4, s81, v5
	global_store_dword v[2:3], v4, off
	v_lshl_add_u64 v[2:3], s[20:21], 0, v[96:97]
	v_lshlrev_b64 v[4:5], 13, v[2:3]
	v_lshl_add_u64 v[4:5], s[68:69], 0, v[4:5]
	v_lshl_add_u64 v[4:5], v[4:5], 0, s[24:25]
	v_lshl_add_u64 v[4:5], v[4:5], 0, v[156:157]
	v_add_co_u32_e32 v4, vcc, s33, v4
	v_lshlrev_b64 v[2:3], 12, v[2:3]
	s_nop 0
	v_addc_co_u32_e32 v5, vcc, 0, v5, vcc
	v_mov_b32_e32 v4, v224
	ds_read_b32 v5, v150 offset:17408
	v_lshl_add_u64 v[2:3], v[0:1], 0, v[2:3]
	s_waitcnt lgkmcnt(0)
	v_lshlrev_b32_e32 v6, 16, v5
	v_and_b32_e32 v5, 0xffff0000, v5
	v_lshlrev_b32_e32 v7, 16, v4
	v_mul_f32_e32 v8, 0x3d372713, v7
	v_mul_f32_e32 v8, v8, v7
	v_fma_f32 v8, v8, v7, v7
	v_mul_f32_e32 v8, 0x3f4c422a, v8
	v_mul_f32_e32 v8, -2.0, v8
	v_mul_f32_e32 v8, 0x3fb8aa3b, v8
	v_exp_f32_e32 v8, v8
	v_and_b32_e32 v4, 0xffff0000, v4
	v_add_f32_e32 v8, 1.0, v8
	v_div_scale_f32 v9, s[22:23], v8, v8, v7
	v_rcp_f32_e32 v10, v9
	s_nop 0
	v_fma_f32 v11, -v9, v10, 1.0
	v_fmac_f32_e32 v10, v11, v10
	v_div_scale_f32 v11, vcc, v7, v8, v7
	v_mul_f32_e32 v12, v11, v10
	v_fma_f32 v13, -v9, v12, v11
	v_fmac_f32_e32 v12, v13, v10
	v_fma_f32 v9, -v9, v12, v11
	v_div_fmas_f32 v9, v9, v10, v12
	v_div_fixup_f32 v7, v9, v8, v7
	v_mul_f32_e32 v6, v7, v6
	v_mul_f32_e32 v7, 0x3d372713, v4
	v_mul_f32_e32 v7, v7, v4
	v_fma_f32 v7, v7, v4, v4
	v_mul_f32_e32 v7, 0x3f4c422a, v7
	v_mul_f32_e32 v7, -2.0, v7
	v_mul_f32_e32 v7, 0x3fb8aa3b, v7
	v_exp_f32_e32 v7, v7
	s_nop 0
	v_add_f32_e32 v7, 1.0, v7
	v_div_scale_f32 v8, s[22:23], v7, v7, v4
	v_rcp_f32_e32 v9, v8
	s_nop 0
	v_fma_f32 v10, -v8, v9, 1.0
	v_fmac_f32_e32 v9, v10, v9
	v_div_scale_f32 v10, vcc, v4, v7, v4
	v_mul_f32_e32 v11, v10, v9
	v_fma_f32 v12, -v8, v11, v10
	v_fmac_f32_e32 v11, v12, v9
	v_fma_f32 v8, -v8, v11, v10
	v_div_fmas_f32 v8, v8, v9, v11
	v_div_fixup_f32 v4, v8, v7, v4
	v_mul_f32_e32 v4, v4, v5
	v_bfe_u32 v5, v6, 16, 1
	v_add3_u32 v5, v6, v5, s71
	v_bfe_u32 v6, v4, 16, 1
	v_lshrrev_b32_e32 v5, 16, v5
	v_add3_u32 v4, v4, v6, s71
	v_and_or_b32 v4, v4, s81, v5
	global_store_dword v[2:3], v4, off
	v_lshl_add_u64 v[2:3], s[20:21], 0, v[98:99]
	v_lshlrev_b64 v[4:5], 13, v[2:3]
	v_lshl_add_u64 v[4:5], s[68:69], 0, v[4:5]
	v_lshl_add_u64 v[4:5], v[4:5], 0, s[24:25]
	v_lshl_add_u64 v[4:5], v[4:5], 0, v[156:157]
	v_add_co_u32_e32 v4, vcc, s33, v4
	v_lshlrev_b64 v[2:3], 12, v[2:3]
	s_nop 0
	v_addc_co_u32_e32 v5, vcc, 0, v5, vcc
	v_mov_b32_e32 v4, v225
	ds_read_b32 v5, v151 offset:17408
	v_lshl_add_u64 v[2:3], v[0:1], 0, v[2:3]
	s_waitcnt lgkmcnt(0)
; DEV unsigned pack2(float a, float b) { return (unsigned)f2bf(a) | ((unsigned)f2bf(b) << 16); }
; DEV float lo2f(unsigned v) { return __uint_as_float(v << 16); }
; DEV float hi2f(unsigned v) { return __uint_as_float(v & 0xffff0000u); }
; DEV float gelu_tanh(float x) {
;   float u = 0.7978845608028654f * (x + 0.044715f * x * x * x);
;   return x / (1.f + __expf(-2.f * u));
; }
; PHASE void lru_phase(const Params& p, int layer, const u16* __restrict__ GC, u16* __restrict__ OC, float* __restrict__ LA, ...
;     ...
; #pragma unroll
;       for (int i = 0; i < 16; ++i) {
;         const int t = tg * 16 + i;
;         const unsigned yv = *(const unsigned*)(GC + (base + t0 + t) * 4096 + 2048 + ch0 + 2 * cp);
;         const unsigned hv = *(const unsigned*)(sR + t * 128 + 2 * cp);
;         *(unsigned*)(OC + (base + t0 + t) * 2048 + ch0 + 2 * cp) =
;             pack2(lo2f(hv) * gelu_tanh(lo2f(yv)), hi2f(hv) * gelu_tanh(hi2f(yv)));
;       }
	v_lshlrev_b32_e32 v6, 16, v5
	v_and_b32_e32 v5, 0xffff0000, v5
	v_lshlrev_b32_e32 v7, 16, v4
	v_mul_f32_e32 v8, 0x3d372713, v7
	v_mul_f32_e32 v8, v8, v7
	v_fma_f32 v8, v8, v7, v7
	v_mul_f32_e32 v8, 0x3f4c422a, v8
	v_mul_f32_e32 v8, -2.0, v8
	v_mul_f32_e32 v8, 0x3fb8aa3b, v8
	v_exp_f32_e32 v8, v8
	v_and_b32_e32 v4, 0xffff0000, v4
	v_add_f32_e32 v8, 1.0, v8
	v_div_scale_f32 v9, s[22:23], v8, v8, v7
	v_rcp_f32_e32 v10, v9
	s_nop 0
	v_fma_f32 v11, -v9, v10, 1.0
	v_fmac_f32_e32 v10, v11, v10
	v_div_scale_f32 v11, vcc, v7, v8, v7
	v_mul_f32_e32 v12, v11, v10
	v_fma_f32 v13, -v9, v12, v11
	v_fmac_f32_e32 v12, v13, v10
	v_fma_f32 v9, -v9, v12, v11
	v_div_fmas_f32 v9, v9, v10, v12
	v_div_fixup_f32 v7, v9, v8, v7
	v_mul_f32_e32 v6, v7, v6
	v_mul_f32_e32 v7, 0x3d372713, v4
	v_mul_f32_e32 v7, v7, v4
	v_fma_f32 v7, v7, v4, v4
	v_mul_f32_e32 v7, 0x3f4c422a, v7
	v_mul_f32_e32 v7, -2.0, v7
	v_mul_f32_e32 v7, 0x3fb8aa3b, v7
	v_exp_f32_e32 v7, v7
	s_nop 0
	v_add_f32_e32 v7, 1.0, v7
	v_div_scale_f32 v8, s[22:23], v7, v7, v4
	v_rcp_f32_e32 v9, v8
	s_nop 0
	v_fma_f32 v10, -v8, v9, 1.0
	v_fmac_f32_e32 v9, v10, v9
	v_div_scale_f32 v10, vcc, v4, v7, v4
	v_mul_f32_e32 v11, v10, v9
	v_fma_f32 v12, -v8, v11, v10
	v_fmac_f32_e32 v11, v12, v9
	v_fma_f32 v8, -v8, v11, v10
	v_div_fmas_f32 v8, v8, v9, v11
	v_div_fixup_f32 v4, v8, v7, v4
	v_mul_f32_e32 v4, v4, v5
	v_bfe_u32 v5, v6, 16, 1
	v_add3_u32 v5, v6, v5, s71
	v_bfe_u32 v6, v4, 16, 1
	v_lshrrev_b32_e32 v5, 16, v5
	v_add3_u32 v4, v4, v6, s71
	v_and_or_b32 v4, v4, s81, v5
	global_store_dword v[2:3], v4, off
	v_lshl_add_u64 v[2:3], s[20:21], 0, v[100:101]
	v_lshlrev_b64 v[4:5], 13, v[2:3]
	v_lshl_add_u64 v[4:5], s[68:69], 0, v[4:5]
	v_lshl_add_u64 v[4:5], v[4:5], 0, s[24:25]
	v_lshl_add_u64 v[4:5], v[4:5], 0, v[156:157]
	v_add_co_u32_e32 v4, vcc, s33, v4
	v_lshlrev_b64 v[2:3], 12, v[2:3]
	s_nop 0
	v_addc_co_u32_e32 v5, vcc, 0, v5, vcc
	v_mov_b32_e32 v4, v226
	ds_read_b32 v5, v152 offset:17408
	v_lshl_add_u64 v[2:3], v[0:1], 0, v[2:3]
	s_waitcnt lgkmcnt(0)
	v_lshlrev_b32_e32 v6, 16, v5
	v_and_b32_e32 v5, 0xffff0000, v5
	v_lshlrev_b32_e32 v7, 16, v4
	v_mul_f32_e32 v8, 0x3d372713, v7
	v_mul_f32_e32 v8, v8, v7
	v_fma_f32 v8, v8, v7, v7
	v_mul_f32_e32 v8, 0x3f4c422a, v8
	v_mul_f32_e32 v8, -2.0, v8
	v_mul_f32_e32 v8, 0x3fb8aa3b, v8
	v_exp_f32_e32 v8, v8
	v_and_b32_e32 v4, 0xffff0000, v4
	v_add_f32_e32 v8, 1.0, v8
	v_div_scale_f32 v9, s[22:23], v8, v8, v7
	v_rcp_f32_e32 v10, v9
	s_nop 0
	v_fma_f32 v11, -v9, v10, 1.0
	v_fmac_f32_e32 v10, v11, v10
	v_div_scale_f32 v11, vcc, v7, v8, v7
	v_mul_f32_e32 v12, v11, v10
	v_fma_f32 v13, -v9, v12, v11
	v_fmac_f32_e32 v12, v13, v10
	v_fma_f32 v9, -v9, v12, v11
	v_div_fmas_f32 v9, v9, v10, v12
	v_div_fixup_f32 v7, v9, v8, v7
	v_mul_f32_e32 v6, v7, v6
	v_mul_f32_e32 v7, 0x3d372713, v4
	v_mul_f32_e32 v7, v7, v4
	v_fma_f32 v7, v7, v4, v4
	v_mul_f32_e32 v7, 0x3f4c422a, v7
	v_mul_f32_e32 v7, -2.0, v7
	v_mul_f32_e32 v7, 0x3fb8aa3b, v7
	v_exp_f32_e32 v7, v7
	s_nop 0
	v_add_f32_e32 v7, 1.0, v7
	v_div_scale_f32 v8, s[22:23], v7, v7, v4
	v_rcp_f32_e32 v9, v8
	s_nop 0
	v_fma_f32 v10, -v8, v9, 1.0
	v_fmac_f32_e32 v9, v10, v9
	v_div_scale_f32 v10, vcc, v4, v7, v4
	v_mul_f32_e32 v11, v10, v9
	v_fma_f32 v12, -v8, v11, v10
	v_fmac_f32_e32 v11, v12, v9
	v_fma_f32 v8, -v8, v11, v10
	v_div_fmas_f32 v8, v8, v9, v11
	v_div_fixup_f32 v4, v8, v7, v4
	v_mul_f32_e32 v4, v4, v5
	v_bfe_u32 v5, v6, 16, 1
	v_add3_u32 v5, v6, v5, s71
	v_bfe_u32 v6, v4, 16, 1
	v_lshrrev_b32_e32 v5, 16, v5
	v_add3_u32 v4, v4, v6, s71
	v_and_or_b32 v4, v4, s81, v5
	global_store_dword v[2:3], v4, off
	v_lshl_add_u64 v[2:3], s[20:21], 0, v[102:103]
	v_lshlrev_b64 v[4:5], 13, v[2:3]
	v_lshl_add_u64 v[4:5], s[68:69], 0, v[4:5]
	v_lshl_add_u64 v[4:5], v[4:5], 0, s[24:25]
	v_lshl_add_u64 v[4:5], v[4:5], 0, v[156:157]
	v_add_co_u32_e32 v4, vcc, s33, v4
	s_mov_b32 s21, s25
	s_nop 0
	v_addc_co_u32_e32 v5, vcc, 0, v5, vcc
	v_mov_b32_e32 v4, v227
	v_writelane_b32 v249, s20, 62
	ds_read_b32 v5, v153 offset:17408
	v_lshlrev_b64 v[2:3], 12, v[2:3]
	v_writelane_b32 v249, s21, 63
	v_lshl_add_u64 v[0:1], v[0:1], 0, v[2:3]
	s_waitcnt lgkmcnt(0)
	v_lshlrev_b32_e32 v6, 16, v5
	v_and_b32_e32 v5, 0xffff0000, v5
	v_lshlrev_b32_e32 v7, 16, v4
	v_mul_f32_e32 v8, 0x3d372713, v7
	v_mul_f32_e32 v8, v8, v7
	v_fma_f32 v8, v8, v7, v7
	v_mul_f32_e32 v8, 0x3f4c422a, v8
	v_mul_f32_e32 v8, -2.0, v8
	v_mul_f32_e32 v8, 0x3fb8aa3b, v8
	v_exp_f32_e32 v8, v8
	v_and_b32_e32 v4, 0xffff0000, v4
	v_add_f32_e32 v8, 1.0, v8
	v_div_scale_f32 v9, s[20:21], v8, v8, v7
	v_rcp_f32_e32 v10, v9
	s_nop 0
	v_fma_f32 v11, -v9, v10, 1.0
	v_fmac_f32_e32 v10, v11, v10
	v_div_scale_f32 v11, vcc, v7, v8, v7
	v_mul_f32_e32 v12, v11, v10
	v_fma_f32 v13, -v9, v12, v11
	v_fmac_f32_e32 v12, v13, v10
	v_fma_f32 v9, -v9, v12, v11
	v_div_fmas_f32 v9, v9, v10, v12
	v_div_fixup_f32 v7, v9, v8, v7
	v_mul_f32_e32 v6, v7, v6
	v_mul_f32_e32 v7, 0x3d372713, v4
	v_mul_f32_e32 v7, v7, v4
	v_fma_f32 v7, v7, v4, v4
	v_mul_f32_e32 v7, 0x3f4c422a, v7
	v_mul_f32_e32 v7, -2.0, v7
	v_mul_f32_e32 v7, 0x3fb8aa3b, v7
	v_exp_f32_e32 v7, v7
	s_nop 0
	v_add_f32_e32 v7, 1.0, v7
	v_div_scale_f32 v8, s[20:21], v7, v7, v4
	v_rcp_f32_e32 v9, v8
	s_nop 0
	v_fma_f32 v10, -v8, v9, 1.0
	v_fmac_f32_e32 v9, v10, v9
	v_div_scale_f32 v10, vcc, v4, v7, v4
	v_mul_f32_e32 v11, v10, v9
	v_fma_f32 v12, -v8, v11, v10
	v_fmac_f32_e32 v11, v12, v9
	v_fma_f32 v8, -v8, v11, v10
	v_div_fmas_f32 v8, v8, v9, v11
	v_div_fixup_f32 v4, v8, v7, v4
	v_mul_f32_e32 v4, v4, v5
	v_bfe_u32 v5, v6, 16, 1
	v_add3_u32 v5, v6, v5, s71
	v_bfe_u32 v6, v4, 16, 1
	v_lshrrev_b32_e32 v5, 16, v5
	v_add3_u32 v4, v4, v6, s71
	v_and_or_b32 v4, v4, s81, v5
	global_store_dword v[0:1], v4, off
	s_branch .LBB0_362
